# K-loop: barrier ending each MFMA segment signalled 3 MFMAs early, trailing MFMAs at raised priority
# baseline (speedup 1.0000x reference)
; #define PG8_STAGE(bufoff, gbase, voff) do { _Pragma("unroll") for (int _i = 0; _i < 2; ++_i) \
;         __builtin_amdgcn_global_load_lds((const unsigned*)((const char*)(gbase) + (voff)[_i]), (PG8_LAS unsigned*)(lds + (bufoff) + ldsw + _i * 8192), 16, 0, 0); } while (0)
; #define PG8_LDA(dst, b, h) do { _Pragma("unroll") for (int m = 0; m < 4; ++m) _Pragma("unroll") for (int k = 0; k < 2; ++k) dst[m][k] = *(const PG8_LAS bf16x8*)(lds + PG8_SA(b, h) + aoff + m * 2048 + k * 1024); } while (0)
; #define PG8_LDB(dst, b, h) do { _Pragma("unroll") for (int n = 0; n < 2; ++n) _Pragma("unroll") for (int k = 0; k < 2; ++k) dst[n][k] = *(const PG8_LAS bf16x8*)(lds + PG8_SB(b, h) + boff + n * 2048 + k * 1024); } while (0)
; #define PG8_MMA(ai, bj, At, Bt) do { __builtin_amdgcn_s_setprio(1); _Pragma("unroll") for (int m = 0; m < 4; ++m) _Pragma("unroll") for (int n = 0; n < 2; ++n) _Pragma("unroll") for (int k = 0; k < 2; ++k) \
;         acc[ai][bj][m][n] = __builtin_amdgcn_mfma_f32_16x16x32_bf16(Bt[n][k], At[m][k], acc[ai][bj][m][n], 0, 0, 0); __builtin_amdgcn_s_setprio(0); } while (0)
; #define PG8_WAIT_V(n) asm volatile("s_waitcnt vmcnt(" #n ")" ::: "memory")
; #define PG8_WAIT_L(n) asm volatile("s_waitcnt lgkmcnt(" #n ")" ::: "memory")
; template <class Epi, class Sched, bool ALIGN_EPI = false, bool SP2 = false>
; __device__ __forceinline__ void gemm_phase(PG8_LAS unsigned char* lds, const Gemm g, const Sched& S, const Epi& E) {
;     ...
;             const bool last = (t == nt - 2);
;             const char* a1 = cA + (size_t)(t + 1) * kstep;
;             const char* a2 = last ? nA : cA + (size_t)(t + 2) * kstep; const char* b2 = last ? nB : cB + (size_t)(t + 2) * kstep;
;             const char* a3 = a2 + kstep; const char* b3 = b2 + kstep;
;             if (last && has_next) S.a_ready(nxt);
;             if constexpr (SP2) {
;             PG8_LDB(B0, 0, 0); PG8_LDB(B1, 0, 1); PG8_SCHED; PG8_LDA(At, 0, 0); PG8_STAGE(PG8_SA(1, 1), a1 + hstep, voffA);
;             PG8_WAIT_V(8); PG8_WAIT_L(0); PG8_BAR; PG8_MMA(0, 0, At, B0); PG8_MMA(0, 1, At, B1); PG8_BAR; PG8_SCHED;
;             PG8_LDA(At, 0, 1); PG8_STAGE(PG8_SB(0, 0), b2, voffB); PG8_STAGE(PG8_SB(0, 1), b2 + hstep, voffB); PG8_STAGE(PG8_SA(0, 0), a2, voffA);
;             PG8_WAIT_V(8); PG8_WAIT_L(0); PG8_BAR; PG8_MMA(1, 0, At, B0); PG8_MMA(1, 1, At, B1); PG8_BAR; PG8_SCHED;
.LBB0_166:
	s_add_u32 s24, s22, 0xfffc0080
	s_addc_u32 s25, s23, -1
	s_add_i32 s59, 0, 0x10000
	s_cmp_eq_u32 s58, 12
	s_cselect_b32 s27, s11, s25
	s_cselect_b32 s26, s15, s24
	v_add_u32_e32 v0, s59, v202
	s_cselect_b32 s25, s13, s57
	s_cselect_b32 s24, s21, s56
	s_add_i32 s62, 0, 0x14000
	ds_read_b128 v[130:133], v0
	ds_read_b128 v[134:137], v0 offset:1024
	ds_read_b128 v[138:141], v0 offset:2048
	ds_read_b128 v[142:145], v0 offset:3072
	v_add_u32_e32 v0, s62, v202
	ds_read_b128 v[146:149], v0
	ds_read_b128 v[162:165], v0 offset:1024
	ds_read_b128 v[192:195], v0 offset:2048
	ds_read_b128 v[196:199], v0 offset:3072
	v_lshl_add_u64 v[200:201], s[22:23], 0, v[160:161]
	s_add_i32 m0, s38, 0xc000
	ds_read_b128 v[206:209], v204
	ds_read_b128 v[210:213], v204 offset:1024
	ds_read_b128 v[214:217], v204 offset:2048
	ds_read_b128 v[218:221], v204 offset:3072
	ds_read_b128 v[222:225], v204 offset:4096
	ds_read_b128 v[226:229], v204 offset:5120
	ds_read_b128 v[230:233], v204 offset:6144
	ds_read_b128 v[244:247], v204 offset:7168
	global_load_lds_dwordx4 v[200:201], off
	v_lshl_add_u64 v[200:201], s[22:23], 0, v[158:159]
	s_add_i32 m0, s38, 0xe000
	s_nop 0
	global_load_lds_dwordx4 v[200:201], off
	s_waitcnt vmcnt(8)
	s_waitcnt lgkmcnt(0)
	s_barrier
	s_setprio 1
	s_waitcnt lgkmcnt(0)
	v_mfma_f32_16x16x32_bf16 v[126:129], v[130:133], v[206:209], v[126:129]
	v_mfma_f32_16x16x32_bf16 v[122:125], v[138:141], v[206:209], v[122:125]
	v_mfma_f32_16x16x32_bf16 v[110:113], v[130:133], v[214:217], v[110:113]
	v_mfma_f32_16x16x32_bf16 v[106:109], v[138:141], v[214:217], v[106:109]
	v_mfma_f32_16x16x32_bf16 v[94:97], v[130:133], v[222:225], v[94:97]
	v_mfma_f32_16x16x32_bf16 v[90:93], v[138:141], v[222:225], v[90:93]
	v_mfma_f32_16x16x32_bf16 v[78:81], v[130:133], v[230:233], v[78:81]
	v_mfma_f32_16x16x32_bf16 v[74:77], v[138:141], v[230:233], v[74:77]
	v_mfma_f32_16x16x32_bf16 v[126:129], v[134:137], v[210:213], v[126:129]
	v_mfma_f32_16x16x32_bf16 v[122:125], v[142:145], v[210:213], v[122:125]
	v_mfma_f32_16x16x32_bf16 v[110:113], v[134:137], v[218:221], v[110:113]
	v_mfma_f32_16x16x32_bf16 v[106:109], v[142:145], v[218:221], v[106:109]
	v_mfma_f32_16x16x32_bf16 v[94:97], v[134:137], v[226:229], v[94:97]
	v_mfma_f32_16x16x32_bf16 v[90:93], v[142:145], v[226:229], v[90:93]
	v_mfma_f32_16x16x32_bf16 v[78:81], v[134:137], v[244:247], v[78:81]
	v_mfma_f32_16x16x32_bf16 v[74:77], v[142:145], v[244:247], v[74:77]
	s_setprio 0
	s_setprio 1
	v_mfma_f32_16x16x32_bf16 v[118:121], v[146:149], v[206:209], v[118:121]
	v_mfma_f32_16x16x32_bf16 v[114:117], v[192:195], v[206:209], v[114:117]
	v_mfma_f32_16x16x32_bf16 v[102:105], v[146:149], v[214:217], v[102:105]
	v_mfma_f32_16x16x32_bf16 v[98:101], v[192:195], v[214:217], v[98:101]
	v_mfma_f32_16x16x32_bf16 v[86:89], v[146:149], v[222:225], v[86:89]
	v_mfma_f32_16x16x32_bf16 v[82:85], v[192:195], v[222:225], v[82:85]
	v_mfma_f32_16x16x32_bf16 v[70:73], v[146:149], v[230:233], v[70:73]
	v_mfma_f32_16x16x32_bf16 v[66:69], v[192:195], v[230:233], v[66:69]
	v_mfma_f32_16x16x32_bf16 v[118:121], v[162:165], v[210:213], v[118:121]
	v_mfma_f32_16x16x32_bf16 v[114:117], v[196:199], v[210:213], v[114:117]
	v_mfma_f32_16x16x32_bf16 v[102:105], v[162:165], v[218:221], v[102:105]
	v_mfma_f32_16x16x32_bf16 v[98:101], v[196:199], v[218:221], v[98:101]
	v_mfma_f32_16x16x32_bf16 v[86:89], v[162:165], v[226:229], v[86:89]
	s_setprio 3
	s_barrier
	v_mfma_f32_16x16x32_bf16 v[82:85], v[196:199], v[226:229], v[82:85]
	v_mfma_f32_16x16x32_bf16 v[70:73], v[162:165], v[244:247], v[70:73]
	v_mfma_f32_16x16x32_bf16 v[66:69], v[196:199], v[244:247], v[66:69]
	s_setprio 0
	s_add_i32 s59, s59, s37
	v_lshl_add_u64 v[200:201], s[24:25], 0, v[152:153]
	s_mov_b32 m0, s59
	ds_read_b128 v[206:209], v204 offset:16384
	ds_read_b128 v[210:213], v204 offset:17408
	ds_read_b128 v[214:217], v204 offset:18432
	ds_read_b128 v[218:221], v204 offset:19456
	ds_read_b128 v[222:225], v204 offset:20480
	ds_read_b128 v[226:229], v204 offset:21504
	ds_read_b128 v[230:233], v204 offset:22528
	ds_read_b128 v[244:247], v204 offset:23552
	global_load_lds_dwordx4 v[200:201], off
	s_add_i32 m0, s59, 0x2000
	s_add_u32 s60, s24, 0x40000
	v_lshl_add_u64 v[248:249], s[24:25], 0, v[156:157]
	s_addc_u32 s61, s25, 0
	s_add_i32 s59, s62, s37
	global_load_lds_dwordx4 v[248:249], off
	v_lshl_add_u64 v[250:251], s[60:61], 0, v[152:153]
	s_mov_b32 m0, s59
	v_lshl_add_u64 v[252:253], s[26:27], 0, v[154:155]
	global_load_lds_dwordx4 v[250:251], off
	v_lshl_add_u64 v[250:251], s[60:61], 0, v[156:157]
	s_add_i32 m0, s59, 0x2000
	s_nop 0
	global_load_lds_dwordx4 v[250:251], off
	v_lshl_add_u64 v[250:251], s[26:27], 0, v[150:151]
	s_mov_b32 m0, s38
	s_nop 0
	global_load_lds_dwordx4 v[250:251], off
	s_mov_b32 m0, s39
	s_nop 0
	global_load_lds_dwordx4 v[252:253], off
	s_waitcnt vmcnt(8)
	s_waitcnt lgkmcnt(0)
	s_barrier
; #define PG8_STAGE(bufoff, gbase, voff) do { _Pragma("unroll") for (int _i = 0; _i < 2; ++_i) \
;         __builtin_amdgcn_global_load_lds((const unsigned*)((const char*)(gbase) + (voff)[_i]), (PG8_LAS unsigned*)(lds + (bufoff) + ldsw + _i * 8192), 16, 0, 0); } while (0)
; #define PG8_LDA(dst, b, h) do { _Pragma("unroll") for (int m = 0; m < 4; ++m) _Pragma("unroll") for (int k = 0; k < 2; ++k) dst[m][k] = *(const PG8_LAS bf16x8*)(lds + PG8_SA(b, h) + aoff + m * 2048 + k * 1024); } while (0)
; #define PG8_LDB(dst, b, h) do { _Pragma("unroll") for (int n = 0; n < 2; ++n) _Pragma("unroll") for (int k = 0; k < 2; ++k) dst[n][k] = *(const PG8_LAS bf16x8*)(lds + PG8_SB(b, h) + boff + n * 2048 + k * 1024); } while (0)
; #define PG8_MMA(ai, bj, At, Bt) do { __builtin_amdgcn_s_setprio(1); _Pragma("unroll") for (int m = 0; m < 4; ++m) _Pragma("unroll") for (int n = 0; n < 2; ++n) _Pragma("unroll") for (int k = 0; k < 2; ++k) \
;         acc[ai][bj][m][n] = __builtin_amdgcn_mfma_f32_16x16x32_bf16(Bt[n][k], At[m][k], acc[ai][bj][m][n], 0, 0, 0); __builtin_amdgcn_s_setprio(0); } while (0)
; #define PG8_WAIT_V(n) asm volatile("s_waitcnt vmcnt(" #n ")" ::: "memory")
; #define PG8_WAIT_L(n) asm volatile("s_waitcnt lgkmcnt(" #n ")" ::: "memory")
; #define PG8_BAR __builtin_amdgcn_s_barrier()
; #define PG8_SCHED __builtin_amdgcn_sched_barrier(0)
; template <class Epi, class Sched, bool ALIGN_EPI = false, bool SP2 = false>
; __device__ __forceinline__ void gemm_phase(PG8_LAS unsigned char* lds, const Gemm g, const Sched& S, const Epi& E) {
;     ...
;             PG8_WAIT_V(8); PG8_WAIT_L(0); PG8_BAR; PG8_MMA(1, 0, At, B0); PG8_MMA(1, 1, At, B1); PG8_BAR; PG8_SCHED;
;             PG8_LDB(B0, 1, 0); PG8_LDB(B1, 1, 1); PG8_SCHED; PG8_LDA(At, 1, 0); PG8_STAGE(PG8_SA(0, 1), a2 + hstep, voffA);
;             PG8_WAIT_V(8); PG8_WAIT_L(0); PG8_BAR; PG8_MMA(0, 0, At, B0); PG8_MMA(0, 1, At, B1); PG8_BAR; PG8_SCHED;
	s_setprio 1
	s_waitcnt lgkmcnt(0)
	v_mfma_f32_16x16x32_bf16 v[62:65], v[130:133], v[206:209], v[62:65]
	v_mfma_f32_16x16x32_bf16 v[58:61], v[138:141], v[206:209], v[58:61]
	v_mfma_f32_16x16x32_bf16 v[46:49], v[130:133], v[214:217], v[46:49]
	v_mfma_f32_16x16x32_bf16 v[42:45], v[138:141], v[214:217], v[42:45]
	v_mfma_f32_16x16x32_bf16 v[30:33], v[130:133], v[222:225], v[30:33]
	v_mfma_f32_16x16x32_bf16 v[26:29], v[138:141], v[222:225], v[26:29]
	v_mfma_f32_16x16x32_bf16 v[14:17], v[130:133], v[230:233], v[14:17]
	v_mfma_f32_16x16x32_bf16 v[10:13], v[138:141], v[230:233], v[10:13]
	v_mfma_f32_16x16x32_bf16 v[62:65], v[134:137], v[210:213], v[62:65]
	v_mfma_f32_16x16x32_bf16 v[58:61], v[142:145], v[210:213], v[58:61]
	v_mfma_f32_16x16x32_bf16 v[46:49], v[134:137], v[218:221], v[46:49]
	v_mfma_f32_16x16x32_bf16 v[42:45], v[142:145], v[218:221], v[42:45]
	v_mfma_f32_16x16x32_bf16 v[30:33], v[134:137], v[226:229], v[30:33]
	v_mfma_f32_16x16x32_bf16 v[26:29], v[142:145], v[226:229], v[26:29]
	v_mfma_f32_16x16x32_bf16 v[14:17], v[134:137], v[244:247], v[14:17]
	v_mfma_f32_16x16x32_bf16 v[10:13], v[142:145], v[244:247], v[10:13]
	s_setprio 0
	s_setprio 1
	v_mfma_f32_16x16x32_bf16 v[54:57], v[146:149], v[206:209], v[54:57]
	v_mfma_f32_16x16x32_bf16 v[50:53], v[192:195], v[206:209], v[50:53]
	v_mfma_f32_16x16x32_bf16 v[38:41], v[146:149], v[214:217], v[38:41]
	v_mfma_f32_16x16x32_bf16 v[34:37], v[192:195], v[214:217], v[34:37]
	v_mfma_f32_16x16x32_bf16 v[22:25], v[146:149], v[222:225], v[22:25]
	v_mfma_f32_16x16x32_bf16 v[18:21], v[192:195], v[222:225], v[18:21]
	v_mfma_f32_16x16x32_bf16 v[6:9], v[146:149], v[230:233], v[6:9]
	v_mfma_f32_16x16x32_bf16 v[2:5], v[192:195], v[230:233], v[2:5]
	v_mfma_f32_16x16x32_bf16 v[54:57], v[162:165], v[210:213], v[54:57]
	v_mfma_f32_16x16x32_bf16 v[50:53], v[196:199], v[210:213], v[50:53]
	v_mfma_f32_16x16x32_bf16 v[38:41], v[162:165], v[218:221], v[38:41]
	v_mfma_f32_16x16x32_bf16 v[34:37], v[196:199], v[218:221], v[34:37]
	v_mfma_f32_16x16x32_bf16 v[22:25], v[162:165], v[226:229], v[22:25]
	s_setprio 3
	s_barrier
	v_mfma_f32_16x16x32_bf16 v[18:21], v[196:199], v[226:229], v[18:21]
	v_mfma_f32_16x16x32_bf16 v[6:9], v[162:165], v[244:247], v[6:9]
	v_mfma_f32_16x16x32_bf16 v[2:5], v[196:199], v[244:247], v[2:5]
	s_setprio 0
	s_add_i32 s59, 0, 0x18000
	v_add_u32_e32 v0, s59, v202
	s_add_i32 s60, 0, 0x1c000
	ds_read_b128 v[130:133], v0
	ds_read_b128 v[134:137], v0 offset:1024
	ds_read_b128 v[138:141], v0 offset:2048
	ds_read_b128 v[142:145], v0 offset:3072
	v_add_u32_e32 v0, s60, v202
	ds_read_b128 v[146:149], v0
	ds_read_b128 v[162:165], v0 offset:1024
	ds_read_b128 v[192:195], v0 offset:2048
	ds_read_b128 v[196:199], v0 offset:3072
	s_add_u32 s26, s26, 0x40000
	s_addc_u32 s27, s27, 0
	s_mov_b32 m0, s40
	v_lshl_add_u64 v[236:237], s[26:27], 0, v[150:151]
	ds_read_b128 v[206:209], v204 offset:32768
	ds_read_b128 v[210:213], v204 offset:33792
	ds_read_b128 v[214:217], v204 offset:34816
	ds_read_b128 v[218:221], v204 offset:35840
	ds_read_b128 v[222:225], v204 offset:36864
	ds_read_b128 v[226:229], v204 offset:37888
	ds_read_b128 v[230:233], v204 offset:38912
	ds_read_b128 v[244:247], v204 offset:39936
	global_load_lds_dwordx4 v[236:237], off
	v_lshl_add_u64 v[236:237], s[26:27], 0, v[154:155]
	s_mov_b32 m0, s41
	s_nop 0
	global_load_lds_dwordx4 v[236:237], off
	s_waitcnt vmcnt(8)
	s_waitcnt lgkmcnt(0)
	s_barrier
	s_setprio 1
	s_waitcnt lgkmcnt(0)
	v_mfma_f32_16x16x32_bf16 v[126:129], v[130:133], v[206:209], v[126:129]
	v_mfma_f32_16x16x32_bf16 v[122:125], v[138:141], v[206:209], v[122:125]
	v_mfma_f32_16x16x32_bf16 v[110:113], v[130:133], v[214:217], v[110:113]
	v_mfma_f32_16x16x32_bf16 v[106:109], v[138:141], v[214:217], v[106:109]
	v_mfma_f32_16x16x32_bf16 v[94:97], v[130:133], v[222:225], v[94:97]
	v_mfma_f32_16x16x32_bf16 v[90:93], v[138:141], v[222:225], v[90:93]
	v_mfma_f32_16x16x32_bf16 v[78:81], v[130:133], v[230:233], v[78:81]
	v_mfma_f32_16x16x32_bf16 v[74:77], v[138:141], v[230:233], v[74:77]
	v_mfma_f32_16x16x32_bf16 v[126:129], v[134:137], v[210:213], v[126:129]
	v_mfma_f32_16x16x32_bf16 v[122:125], v[142:145], v[210:213], v[122:125]
	v_mfma_f32_16x16x32_bf16 v[110:113], v[134:137], v[218:221], v[110:113]
	v_mfma_f32_16x16x32_bf16 v[106:109], v[142:145], v[218:221], v[106:109]
	v_mfma_f32_16x16x32_bf16 v[94:97], v[134:137], v[226:229], v[94:97]
	v_mfma_f32_16x16x32_bf16 v[90:93], v[142:145], v[226:229], v[90:93]
	v_mfma_f32_16x16x32_bf16 v[78:81], v[134:137], v[244:247], v[78:81]
	v_mfma_f32_16x16x32_bf16 v[74:77], v[142:145], v[244:247], v[74:77]
	s_setprio 0
	s_setprio 1
	v_mfma_f32_16x16x32_bf16 v[118:121], v[146:149], v[206:209], v[118:121]
	v_mfma_f32_16x16x32_bf16 v[114:117], v[192:195], v[206:209], v[114:117]
	v_mfma_f32_16x16x32_bf16 v[102:105], v[146:149], v[214:217], v[102:105]
	v_mfma_f32_16x16x32_bf16 v[98:101], v[192:195], v[214:217], v[98:101]
	v_mfma_f32_16x16x32_bf16 v[86:89], v[146:149], v[222:225], v[86:89]
	v_mfma_f32_16x16x32_bf16 v[82:85], v[192:195], v[222:225], v[82:85]
	v_mfma_f32_16x16x32_bf16 v[70:73], v[146:149], v[230:233], v[70:73]
	v_mfma_f32_16x16x32_bf16 v[66:69], v[192:195], v[230:233], v[66:69]
	v_mfma_f32_16x16x32_bf16 v[118:121], v[162:165], v[210:213], v[118:121]
	v_mfma_f32_16x16x32_bf16 v[114:117], v[196:199], v[210:213], v[114:117]
	v_mfma_f32_16x16x32_bf16 v[102:105], v[162:165], v[218:221], v[102:105]
	v_mfma_f32_16x16x32_bf16 v[98:101], v[196:199], v[218:221], v[98:101]
	v_mfma_f32_16x16x32_bf16 v[86:89], v[162:165], v[226:229], v[86:89]
	s_setprio 3
	s_barrier
; #define PG8_STAGE(bufoff, gbase, voff) do { _Pragma("unroll") for (int _i = 0; _i < 2; ++_i) \
;         __builtin_amdgcn_global_load_lds((const unsigned*)((const char*)(gbase) + (voff)[_i]), (PG8_LAS unsigned*)(lds + (bufoff) + ldsw + _i * 8192), 16, 0, 0); } while (0)
; #define PG8_LDA(dst, b, h) do { _Pragma("unroll") for (int m = 0; m < 4; ++m) _Pragma("unroll") for (int k = 0; k < 2; ++k) dst[m][k] = *(const PG8_LAS bf16x8*)(lds + PG8_SA(b, h) + aoff + m * 2048 + k * 1024); } while (0)
; #define PG8_MMA(ai, bj, At, Bt) do { __builtin_amdgcn_s_setprio(1); _Pragma("unroll") for (int m = 0; m < 4; ++m) _Pragma("unroll") for (int n = 0; n < 2; ++n) _Pragma("unroll") for (int k = 0; k < 2; ++k) \
;         acc[ai][bj][m][n] = __builtin_amdgcn_mfma_f32_16x16x32_bf16(Bt[n][k], At[m][k], acc[ai][bj][m][n], 0, 0, 0); __builtin_amdgcn_s_setprio(0); } while (0)
; #define PG8_WAIT_V(n) asm volatile("s_waitcnt vmcnt(" #n ")" ::: "memory")
; #define PG8_WAIT_L(n) asm volatile("s_waitcnt lgkmcnt(" #n ")" ::: "memory")
; #define PG8_BAR __builtin_amdgcn_s_barrier()
; #define PG8_SCHED __builtin_amdgcn_sched_barrier(0)
; template <class Epi, class Sched, bool ALIGN_EPI = false, bool SP2 = false>
; __device__ __forceinline__ void gemm_phase(PG8_LAS unsigned char* lds, const Gemm g, const Sched& S, const Epi& E) {
;     ...
;         for (int t = 0; t < nt; t += 2) {
;     ...
;             PG8_WAIT_V(8); PG8_WAIT_L(0); PG8_BAR; PG8_MMA(0, 0, At, B0); PG8_MMA(0, 1, At, B1); PG8_BAR; PG8_SCHED;
;             PG8_LDA(At, 1, 1); PG8_STAGE(PG8_SB(1, 0), b3, voffB); PG8_STAGE(PG8_SB(1, 1), b3 + hstep, voffB); PG8_STAGE(PG8_SA(1, 0), a3, voffA);
;             PG8_WAIT_V(8); PG8_WAIT_L(0); PG8_BAR; PG8_MMA(1, 0, At, B0); PG8_MMA(1, 1, At, B1); PG8_BAR; PG8_SCHED;
	v_mfma_f32_16x16x32_bf16 v[82:85], v[196:199], v[226:229], v[82:85]
	v_mfma_f32_16x16x32_bf16 v[70:73], v[162:165], v[244:247], v[70:73]
	v_mfma_f32_16x16x32_bf16 v[66:69], v[196:199], v[244:247], v[66:69]
	s_setprio 0
	s_add_i32 s26, s59, s37
	v_lshl_add_u64 v[200:201], v[200:201], 0, vcc
	s_mov_b32 m0, s26
	ds_read_b128 v[206:209], v204 offset:49152
	ds_read_b128 v[210:213], v204 offset:50176
	ds_read_b128 v[214:217], v204 offset:51200
	ds_read_b128 v[218:221], v204 offset:52224
	ds_read_b128 v[222:225], v204 offset:53248
	ds_read_b128 v[226:229], v204 offset:54272
	ds_read_b128 v[230:233], v204 offset:55296
	ds_read_b128 v[244:247], v204 offset:56320
	global_load_lds_dwordx4 v[200:201], off
	s_add_i32 m0, s26, 0x2000
	s_add_u32 s24, s24, 0x40080
	v_lshl_add_u64 v[200:201], v[248:249], 0, vcc
	s_addc_u32 s25, s25, 0
	s_add_i32 s26, s60, s37
	global_load_lds_dwordx4 v[200:201], off
	v_lshl_add_u64 v[200:201], s[24:25], 0, v[152:153]
	s_mov_b32 m0, s26
	s_nop 0
	global_load_lds_dwordx4 v[200:201], off
	v_lshl_add_u64 v[200:201], s[24:25], 0, v[156:157]
	s_add_i32 m0, s26, 0x2000
	s_nop 0
	global_load_lds_dwordx4 v[200:201], off
	v_lshl_add_u64 v[200:201], v[250:251], 0, vcc
	s_mov_b32 m0, s51
	s_nop 0
	global_load_lds_dwordx4 v[200:201], off
	v_lshl_add_u64 v[200:201], v[252:253], 0, vcc
	s_mov_b32 m0, s52
	s_nop 0
	global_load_lds_dwordx4 v[200:201], off
	s_waitcnt vmcnt(8)
	s_waitcnt lgkmcnt(0)
	s_barrier
	s_setprio 1
	s_waitcnt lgkmcnt(0)
	v_mfma_f32_16x16x32_bf16 v[62:65], v[130:133], v[206:209], v[62:65]
	v_mfma_f32_16x16x32_bf16 v[58:61], v[138:141], v[206:209], v[58:61]
	v_mfma_f32_16x16x32_bf16 v[46:49], v[130:133], v[214:217], v[46:49]
	v_mfma_f32_16x16x32_bf16 v[42:45], v[138:141], v[214:217], v[42:45]
	v_mfma_f32_16x16x32_bf16 v[30:33], v[130:133], v[222:225], v[30:33]
	v_mfma_f32_16x16x32_bf16 v[26:29], v[138:141], v[222:225], v[26:29]
	v_mfma_f32_16x16x32_bf16 v[14:17], v[130:133], v[230:233], v[14:17]
	v_mfma_f32_16x16x32_bf16 v[10:13], v[138:141], v[230:233], v[10:13]
	v_mfma_f32_16x16x32_bf16 v[62:65], v[134:137], v[210:213], v[62:65]
	v_mfma_f32_16x16x32_bf16 v[58:61], v[142:145], v[210:213], v[58:61]
	v_mfma_f32_16x16x32_bf16 v[46:49], v[134:137], v[218:221], v[46:49]
	v_mfma_f32_16x16x32_bf16 v[42:45], v[142:145], v[218:221], v[42:45]
	v_mfma_f32_16x16x32_bf16 v[30:33], v[134:137], v[226:229], v[30:33]
	v_mfma_f32_16x16x32_bf16 v[26:29], v[142:145], v[226:229], v[26:29]
	v_mfma_f32_16x16x32_bf16 v[14:17], v[134:137], v[244:247], v[14:17]
	v_mfma_f32_16x16x32_bf16 v[10:13], v[142:145], v[244:247], v[10:13]
	s_setprio 0
	s_setprio 1
	v_mfma_f32_16x16x32_bf16 v[54:57], v[146:149], v[206:209], v[54:57]
	v_mfma_f32_16x16x32_bf16 v[50:53], v[192:195], v[206:209], v[50:53]
	v_mfma_f32_16x16x32_bf16 v[38:41], v[146:149], v[214:217], v[38:41]
	v_mfma_f32_16x16x32_bf16 v[34:37], v[192:195], v[214:217], v[34:37]
	v_mfma_f32_16x16x32_bf16 v[22:25], v[146:149], v[222:225], v[22:25]
	v_mfma_f32_16x16x32_bf16 v[18:21], v[192:195], v[222:225], v[18:21]
	v_mfma_f32_16x16x32_bf16 v[6:9], v[146:149], v[230:233], v[6:9]
	v_mfma_f32_16x16x32_bf16 v[2:5], v[192:195], v[230:233], v[2:5]
	v_mfma_f32_16x16x32_bf16 v[54:57], v[162:165], v[210:213], v[54:57]
	v_mfma_f32_16x16x32_bf16 v[50:53], v[196:199], v[210:213], v[50:53]
	v_mfma_f32_16x16x32_bf16 v[38:41], v[162:165], v[218:221], v[38:41]
	v_mfma_f32_16x16x32_bf16 v[34:37], v[196:199], v[218:221], v[34:37]
	v_mfma_f32_16x16x32_bf16 v[22:25], v[162:165], v[226:229], v[22:25]
	s_setprio 3
	s_barrier
	v_mfma_f32_16x16x32_bf16 v[18:21], v[196:199], v[226:229], v[18:21]
	v_mfma_f32_16x16x32_bf16 v[6:9], v[162:165], v[244:247], v[6:9]
	v_mfma_f32_16x16x32_bf16 v[2:5], v[196:199], v[244:247], v[2:5]
	s_setprio 0
	s_add_i32 s58, s58, 2
	s_add_u32 s56, s56, 0x100
	s_addc_u32 s57, s57, 0
	s_add_u32 s22, s22, 0x100
	s_addc_u32 s23, s23, 0
	s_cmp_gt_u32 s58, 13
	s_cbranch_scc0 .LBB0_166
	s_and_b64 vcc, exec, s[4:5]
	s_cbranch_vccnz .LBB0_170
	s_mov_b64 s[22:23], -1
	s_cmp_gt_i32 s10, 17
	v_lshl_add_u32 v162, s20, 8, v182
	s_cbranch_scc1 .LBB0_171

; #define PG8_STAGE(bufoff, gbase, voff) do { _Pragma("unroll") for (int _i = 0; _i < 2; ++_i) \
;         __builtin_amdgcn_global_load_lds((const unsigned*)((const char*)(gbase) + (voff)[_i]), (PG8_LAS unsigned*)(lds + (bufoff) + ldsw + _i * 8192), 16, 0, 0); } while (0)
; #define PG8_LDA(dst, b, h) do { _Pragma("unroll") for (int m = 0; m < 4; ++m) _Pragma("unroll") for (int k = 0; k < 2; ++k) dst[m][k] = *(const PG8_LAS bf16x8*)(lds + PG8_SA(b, h) + aoff + m * 2048 + k * 1024); } while (0)
; #define PG8_LDB(dst, b, h) do { _Pragma("unroll") for (int n = 0; n < 2; ++n) _Pragma("unroll") for (int k = 0; k < 2; ++k) dst[n][k] = *(const PG8_LAS bf16x8*)(lds + PG8_SB(b, h) + boff + n * 2048 + k * 1024); } while (0)
; #define PG8_MMA(ai, bj, At, Bt) do { __builtin_amdgcn_s_setprio(1); _Pragma("unroll") for (int m = 0; m < 4; ++m) _Pragma("unroll") for (int n = 0; n < 2; ++n) _Pragma("unroll") for (int k = 0; k < 2; ++k) \
;         acc[ai][bj][m][n] = __builtin_amdgcn_mfma_f32_16x16x32_bf16(Bt[n][k], At[m][k], acc[ai][bj][m][n], 0, 0, 0); __builtin_amdgcn_s_setprio(0); } while (0)
; #define PG8_WAIT_V(n) asm volatile("s_waitcnt vmcnt(" #n ")" ::: "memory")
; #define PG8_WAIT_L(n) asm volatile("s_waitcnt lgkmcnt(" #n ")" ::: "memory")
; template <class Epi, class Sched, bool ALIGN_EPI = false, bool SP2 = false>
; __device__ __forceinline__ void gemm_phase(PG8_LAS unsigned char* lds, const Gemm g, const Sched& S, const Epi& E) {
;     ...
;             const bool last = (t == nt - 2);
;             const char* a1 = cA + (size_t)(t + 1) * kstep;
;             const char* a2 = last ? nA : cA + (size_t)(t + 2) * kstep; const char* b2 = last ? nB : cB + (size_t)(t + 2) * kstep;
;             const char* a3 = a2 + kstep; const char* b3 = b2 + kstep;
;             if (last && has_next) S.a_ready(nxt);
;             if constexpr (SP2) {
;             PG8_LDB(B0, 0, 0); PG8_LDB(B1, 0, 1); PG8_SCHED; PG8_LDA(At, 0, 0); PG8_STAGE(PG8_SA(1, 1), a1 + hstep, voffA);
;             PG8_WAIT_V(8); PG8_WAIT_L(0); PG8_BAR; PG8_MMA(0, 0, At, B0); PG8_MMA(0, 1, At, B1); PG8_BAR; PG8_SCHED;
;             PG8_LDA(At, 0, 1); PG8_STAGE(PG8_SB(0, 0), b2, voffB); PG8_STAGE(PG8_SB(0, 1), b2 + hstep, voffB); PG8_STAGE(PG8_SA(0, 0), a2, voffA);
;             PG8_WAIT_V(8); PG8_WAIT_L(0); PG8_BAR; PG8_MMA(1, 0, At, B0); PG8_MMA(1, 1, At, B1); PG8_BAR; PG8_SCHED;
.LBB0_514:
	s_add_u32 s20, s6, 0xfffe0080
	s_addc_u32 s21, s7, -1
	s_add_i32 s50, 0, 0x10000
	s_cmp_eq_u32 s49, 4
	s_cselect_b32 s23, s11, s21
	s_cselect_b32 s22, s25, s20
	v_add_u32_e32 v0, s50, v159
	s_cselect_b32 s21, s13, s48
	s_cselect_b32 s20, s46, s47
	s_add_i32 s52, 0, 0x14000
	ds_read_b128 v[144:147], v0
	ds_read_b128 v[148:151], v0 offset:1024
	ds_read_b128 v[152:155], v0 offset:2048
	ds_read_b128 v[162:165], v0 offset:3072
	v_add_u32_e32 v0, s52, v159
	ds_read_b128 v[192:195], v0
	ds_read_b128 v[196:199], v0 offset:1024
	ds_read_b128 v[200:203], v0 offset:2048
	ds_read_b128 v[204:207], v0 offset:3072
	v_lshl_add_u64 v[2:3], s[6:7], 0, v[142:143]
	s_add_i32 m0, s9, 0xc000
	ds_read_b128 v[208:211], v161
	ds_read_b128 v[212:215], v161 offset:1024
	ds_read_b128 v[216:219], v161 offset:2048
	ds_read_b128 v[220:223], v161 offset:3072
	ds_read_b128 v[224:227], v161 offset:4096
	ds_read_b128 v[228:231], v161 offset:5120
	ds_read_b128 v[244:247], v161 offset:6144
	ds_read_b128 v[248:251], v161 offset:7168
	global_load_lds_dwordx4 v[2:3], off
	v_lshl_add_u64 v[2:3], s[6:7], 0, v[140:141]
	s_add_i32 m0, s9, 0xe000
	s_nop 0
	global_load_lds_dwordx4 v[2:3], off
	s_waitcnt vmcnt(8)
	s_waitcnt lgkmcnt(0)
	s_barrier
	s_setprio 1
	s_waitcnt lgkmcnt(0)
	v_mfma_f32_16x16x32_bf16 v[128:131], v[144:147], v[208:211], v[128:131]
	v_mfma_f32_16x16x32_bf16 v[124:127], v[152:155], v[208:211], v[124:127]
	v_mfma_f32_16x16x32_bf16 v[120:123], v[144:147], v[216:219], v[120:123]
	v_mfma_f32_16x16x32_bf16 v[116:119], v[152:155], v[216:219], v[116:119]
	v_mfma_f32_16x16x32_bf16 v[112:115], v[144:147], v[224:227], v[112:115]
	v_mfma_f32_16x16x32_bf16 v[108:111], v[152:155], v[224:227], v[108:111]
	v_mfma_f32_16x16x32_bf16 v[104:107], v[144:147], v[244:247], v[104:107]
	v_mfma_f32_16x16x32_bf16 v[100:103], v[152:155], v[244:247], v[100:103]
	v_mfma_f32_16x16x32_bf16 v[128:131], v[148:151], v[212:215], v[128:131]
	v_mfma_f32_16x16x32_bf16 v[124:127], v[162:165], v[212:215], v[124:127]
	v_mfma_f32_16x16x32_bf16 v[120:123], v[148:151], v[220:223], v[120:123]
	v_mfma_f32_16x16x32_bf16 v[116:119], v[162:165], v[220:223], v[116:119]
	v_mfma_f32_16x16x32_bf16 v[112:115], v[148:151], v[228:231], v[112:115]
	v_mfma_f32_16x16x32_bf16 v[108:111], v[162:165], v[228:231], v[108:111]
	v_mfma_f32_16x16x32_bf16 v[104:107], v[148:151], v[248:251], v[104:107]
	v_mfma_f32_16x16x32_bf16 v[100:103], v[162:165], v[248:251], v[100:103]
	s_setprio 0
	s_setprio 1
	v_mfma_f32_16x16x32_bf16 v[96:99], v[192:195], v[208:211], v[96:99]
	v_mfma_f32_16x16x32_bf16 v[92:95], v[200:203], v[208:211], v[92:95]
	v_mfma_f32_16x16x32_bf16 v[88:91], v[192:195], v[216:219], v[88:91]
	v_mfma_f32_16x16x32_bf16 v[84:87], v[200:203], v[216:219], v[84:87]
	v_mfma_f32_16x16x32_bf16 v[80:83], v[192:195], v[224:227], v[80:83]
	v_mfma_f32_16x16x32_bf16 v[76:79], v[200:203], v[224:227], v[76:79]
	v_mfma_f32_16x16x32_bf16 v[72:75], v[192:195], v[244:247], v[72:75]
	v_mfma_f32_16x16x32_bf16 v[68:71], v[200:203], v[244:247], v[68:71]
	v_mfma_f32_16x16x32_bf16 v[96:99], v[196:199], v[212:215], v[96:99]
	v_mfma_f32_16x16x32_bf16 v[92:95], v[204:207], v[212:215], v[92:95]
	v_mfma_f32_16x16x32_bf16 v[88:91], v[196:199], v[220:223], v[88:91]
	v_mfma_f32_16x16x32_bf16 v[84:87], v[204:207], v[220:223], v[84:87]
	v_mfma_f32_16x16x32_bf16 v[80:83], v[196:199], v[228:231], v[80:83]
	s_setprio 3
	s_barrier
	v_mfma_f32_16x16x32_bf16 v[76:79], v[204:207], v[228:231], v[76:79]
	v_mfma_f32_16x16x32_bf16 v[72:75], v[196:199], v[248:251], v[72:75]
	v_mfma_f32_16x16x32_bf16 v[68:71], v[204:207], v[248:251], v[68:71]
	s_setprio 0
	s_add_i32 s50, s50, s30
	v_lshl_add_u64 v[156:157], s[20:21], 0, v[136:137]
	s_mov_b32 m0, s50
	ds_read_b128 v[208:211], v161 offset:16384
	ds_read_b128 v[212:215], v161 offset:17408
	ds_read_b128 v[216:219], v161 offset:18432
	ds_read_b128 v[220:223], v161 offset:19456
	ds_read_b128 v[224:227], v161 offset:20480
	ds_read_b128 v[228:231], v161 offset:21504
	ds_read_b128 v[244:247], v161 offset:22528
	ds_read_b128 v[248:251], v161 offset:23552
	global_load_lds_dwordx4 v[156:157], off
	s_add_i32 m0, s50, 0x2000
	s_add_u32 s50, s20, 0x20000
	v_lshl_add_u64 v[232:233], s[20:21], 0, v[132:133]
	s_addc_u32 s51, s21, 0
	s_add_i32 s52, s52, s30
	global_load_lds_dwordx4 v[232:233], off
	v_lshl_add_u64 v[2:3], s[50:51], 0, v[136:137]
	s_mov_b32 m0, s52
	v_lshl_add_u64 v[236:237], s[22:23], 0, v[138:139]
	global_load_lds_dwordx4 v[2:3], off
	v_lshl_add_u64 v[2:3], s[50:51], 0, v[132:133]
	s_add_i32 m0, s52, 0x2000
	v_lshl_add_u64 v[252:253], s[22:23], 0, v[134:135]
	global_load_lds_dwordx4 v[2:3], off
	s_mov_b32 m0, s9
	s_nop 0
	global_load_lds_dwordx4 v[236:237], off
	s_mov_b32 m0, s36
	s_nop 0
	global_load_lds_dwordx4 v[252:253], off
	s_waitcnt vmcnt(8)
	s_waitcnt lgkmcnt(0)
	s_barrier
; #define PG8_STAGE(bufoff, gbase, voff) do { _Pragma("unroll") for (int _i = 0; _i < 2; ++_i) \
;         __builtin_amdgcn_global_load_lds((const unsigned*)((const char*)(gbase) + (voff)[_i]), (PG8_LAS unsigned*)(lds + (bufoff) + ldsw + _i * 8192), 16, 0, 0); } while (0)
; #define PG8_LDA(dst, b, h) do { _Pragma("unroll") for (int m = 0; m < 4; ++m) _Pragma("unroll") for (int k = 0; k < 2; ++k) dst[m][k] = *(const PG8_LAS bf16x8*)(lds + PG8_SA(b, h) + aoff + m * 2048 + k * 1024); } while (0)
; #define PG8_LDB(dst, b, h) do { _Pragma("unroll") for (int n = 0; n < 2; ++n) _Pragma("unroll") for (int k = 0; k < 2; ++k) dst[n][k] = *(const PG8_LAS bf16x8*)(lds + PG8_SB(b, h) + boff + n * 2048 + k * 1024); } while (0)
; #define PG8_MMA(ai, bj, At, Bt) do { __builtin_amdgcn_s_setprio(1); _Pragma("unroll") for (int m = 0; m < 4; ++m) _Pragma("unroll") for (int n = 0; n < 2; ++n) _Pragma("unroll") for (int k = 0; k < 2; ++k) \
;         acc[ai][bj][m][n] = __builtin_amdgcn_mfma_f32_16x16x32_bf16(Bt[n][k], At[m][k], acc[ai][bj][m][n], 0, 0, 0); __builtin_amdgcn_s_setprio(0); } while (0)
; #define PG8_WAIT_V(n) asm volatile("s_waitcnt vmcnt(" #n ")" ::: "memory")
; #define PG8_WAIT_L(n) asm volatile("s_waitcnt lgkmcnt(" #n ")" ::: "memory")
; #define PG8_BAR __builtin_amdgcn_s_barrier()
; #define PG8_SCHED __builtin_amdgcn_sched_barrier(0)
; template <class Epi, class Sched, bool ALIGN_EPI = false, bool SP2 = false>
; __device__ __forceinline__ void gemm_phase(PG8_LAS unsigned char* lds, const Gemm g, const Sched& S, const Epi& E) {
;     ...
;             PG8_WAIT_V(8); PG8_WAIT_L(0); PG8_BAR; PG8_MMA(1, 0, At, B0); PG8_MMA(1, 1, At, B1); PG8_BAR; PG8_SCHED;
;             PG8_LDB(B0, 1, 0); PG8_LDB(B1, 1, 1); PG8_SCHED; PG8_LDA(At, 1, 0); PG8_STAGE(PG8_SA(0, 1), a2 + hstep, voffA);
;             PG8_WAIT_V(8); PG8_WAIT_L(0); PG8_BAR; PG8_MMA(0, 0, At, B0); PG8_MMA(0, 1, At, B1); PG8_BAR; PG8_SCHED;
	s_setprio 1
	s_waitcnt lgkmcnt(0)
	v_mfma_f32_16x16x32_bf16 v[64:67], v[144:147], v[208:211], v[64:67]
	v_mfma_f32_16x16x32_bf16 v[60:63], v[152:155], v[208:211], v[60:63]
	v_mfma_f32_16x16x32_bf16 v[56:59], v[144:147], v[216:219], v[56:59]
	v_mfma_f32_16x16x32_bf16 v[52:55], v[152:155], v[216:219], v[52:55]
	v_mfma_f32_16x16x32_bf16 v[48:51], v[144:147], v[224:227], v[48:51]
	v_mfma_f32_16x16x32_bf16 v[44:47], v[152:155], v[224:227], v[44:47]
	v_mfma_f32_16x16x32_bf16 v[40:43], v[144:147], v[244:247], v[40:43]
	v_mfma_f32_16x16x32_bf16 v[36:39], v[152:155], v[244:247], v[36:39]
	v_mfma_f32_16x16x32_bf16 v[64:67], v[148:151], v[212:215], v[64:67]
	v_mfma_f32_16x16x32_bf16 v[60:63], v[162:165], v[212:215], v[60:63]
	v_mfma_f32_16x16x32_bf16 v[56:59], v[148:151], v[220:223], v[56:59]
	v_mfma_f32_16x16x32_bf16 v[52:55], v[162:165], v[220:223], v[52:55]
	v_mfma_f32_16x16x32_bf16 v[48:51], v[148:151], v[228:231], v[48:51]
	v_mfma_f32_16x16x32_bf16 v[44:47], v[162:165], v[228:231], v[44:47]
	v_mfma_f32_16x16x32_bf16 v[40:43], v[148:151], v[248:251], v[40:43]
	v_mfma_f32_16x16x32_bf16 v[36:39], v[162:165], v[248:251], v[36:39]
	s_setprio 0
	s_setprio 1
	v_mfma_f32_16x16x32_bf16 v[32:35], v[192:195], v[208:211], v[32:35]
	v_mfma_f32_16x16x32_bf16 v[28:31], v[200:203], v[208:211], v[28:31]
	v_mfma_f32_16x16x32_bf16 v[24:27], v[192:195], v[216:219], v[24:27]
	v_mfma_f32_16x16x32_bf16 v[20:23], v[200:203], v[216:219], v[20:23]
	v_mfma_f32_16x16x32_bf16 v[16:19], v[192:195], v[224:227], v[16:19]
	v_mfma_f32_16x16x32_bf16 v[12:15], v[200:203], v[224:227], v[12:15]
	v_mfma_f32_16x16x32_bf16 v[8:11], v[192:195], v[244:247], v[8:11]
	v_mfma_f32_16x16x32_bf16 v[2:5], v[200:203], v[244:247], v[4:7]
	v_mfma_f32_16x16x32_bf16 v[32:35], v[196:199], v[212:215], v[32:35]
	v_mfma_f32_16x16x32_bf16 v[28:31], v[204:207], v[212:215], v[28:31]
	v_mfma_f32_16x16x32_bf16 v[24:27], v[196:199], v[220:223], v[24:27]
	v_mfma_f32_16x16x32_bf16 v[20:23], v[204:207], v[220:223], v[20:23]
	v_mfma_f32_16x16x32_bf16 v[16:19], v[196:199], v[228:231], v[16:19]
	s_setprio 3
	s_barrier
	v_mfma_f32_16x16x32_bf16 v[12:15], v[204:207], v[228:231], v[12:15]
	v_mfma_f32_16x16x32_bf16 v[8:11], v[196:199], v[248:251], v[8:11]
	v_mfma_f32_16x16x32_bf16 v[2:5], v[204:207], v[248:251], v[2:5]
	s_setprio 0
	s_add_i32 s50, 0, 0x18000
	v_add_u32_e32 v0, s50, v159
	s_add_i32 s51, 0, 0x1c000
	ds_read_b128 v[144:147], v0
	ds_read_b128 v[148:151], v0 offset:1024
	ds_read_b128 v[152:155], v0 offset:2048
	ds_read_b128 v[162:165], v0 offset:3072
	v_add_u32_e32 v0, s51, v159
	ds_read_b128 v[192:195], v0
	ds_read_b128 v[196:199], v0 offset:1024
	ds_read_b128 v[200:203], v0 offset:2048
	ds_read_b128 v[204:207], v0 offset:3072
	s_add_u32 s22, s22, 0x20000
	s_addc_u32 s23, s23, 0
	s_mov_b32 m0, s37
	v_lshl_add_u64 v[6:7], s[22:23], 0, v[138:139]
	ds_read_b128 v[208:211], v161 offset:32768
	ds_read_b128 v[212:215], v161 offset:33792
	ds_read_b128 v[216:219], v161 offset:34816
	ds_read_b128 v[220:223], v161 offset:35840
	ds_read_b128 v[224:227], v161 offset:36864
	ds_read_b128 v[228:231], v161 offset:37888
	ds_read_b128 v[244:247], v161 offset:38912
	ds_read_b128 v[248:251], v161 offset:39936
	global_load_lds_dwordx4 v[6:7], off
	v_lshl_add_u64 v[6:7], s[22:23], 0, v[134:135]
	s_mov_b32 m0, s38
	s_nop 0
	global_load_lds_dwordx4 v[6:7], off
	s_waitcnt vmcnt(8)
	s_waitcnt lgkmcnt(0)
	s_barrier
	s_setprio 1
	s_waitcnt lgkmcnt(0)
	v_mfma_f32_16x16x32_bf16 v[128:131], v[144:147], v[208:211], v[128:131]
	v_mfma_f32_16x16x32_bf16 v[124:127], v[152:155], v[208:211], v[124:127]
	v_mfma_f32_16x16x32_bf16 v[120:123], v[144:147], v[216:219], v[120:123]
	v_mfma_f32_16x16x32_bf16 v[116:119], v[152:155], v[216:219], v[116:119]
	v_mfma_f32_16x16x32_bf16 v[112:115], v[144:147], v[224:227], v[112:115]
	v_mfma_f32_16x16x32_bf16 v[108:111], v[152:155], v[224:227], v[108:111]
	v_mfma_f32_16x16x32_bf16 v[104:107], v[144:147], v[244:247], v[104:107]
	v_mfma_f32_16x16x32_bf16 v[100:103], v[152:155], v[244:247], v[100:103]
	v_mfma_f32_16x16x32_bf16 v[128:131], v[148:151], v[212:215], v[128:131]
	v_mfma_f32_16x16x32_bf16 v[124:127], v[162:165], v[212:215], v[124:127]
	v_mfma_f32_16x16x32_bf16 v[120:123], v[148:151], v[220:223], v[120:123]
	v_mfma_f32_16x16x32_bf16 v[116:119], v[162:165], v[220:223], v[116:119]
	v_mfma_f32_16x16x32_bf16 v[112:115], v[148:151], v[228:231], v[112:115]
	v_mfma_f32_16x16x32_bf16 v[108:111], v[162:165], v[228:231], v[108:111]
	v_mfma_f32_16x16x32_bf16 v[104:107], v[148:151], v[248:251], v[104:107]
	v_mfma_f32_16x16x32_bf16 v[100:103], v[162:165], v[248:251], v[100:103]
	s_setprio 0
	s_setprio 1
	v_mfma_f32_16x16x32_bf16 v[96:99], v[192:195], v[208:211], v[96:99]
	v_mfma_f32_16x16x32_bf16 v[92:95], v[200:203], v[208:211], v[92:95]
	v_mfma_f32_16x16x32_bf16 v[88:91], v[192:195], v[216:219], v[88:91]
	v_mfma_f32_16x16x32_bf16 v[84:87], v[200:203], v[216:219], v[84:87]
	v_mfma_f32_16x16x32_bf16 v[80:83], v[192:195], v[224:227], v[80:83]
	v_mfma_f32_16x16x32_bf16 v[76:79], v[200:203], v[224:227], v[76:79]
	v_mfma_f32_16x16x32_bf16 v[72:75], v[192:195], v[244:247], v[72:75]
	v_mfma_f32_16x16x32_bf16 v[68:71], v[200:203], v[244:247], v[68:71]
	v_mfma_f32_16x16x32_bf16 v[96:99], v[196:199], v[212:215], v[96:99]
	v_mfma_f32_16x16x32_bf16 v[92:95], v[204:207], v[212:215], v[92:95]
	v_mfma_f32_16x16x32_bf16 v[88:91], v[196:199], v[220:223], v[88:91]
	v_mfma_f32_16x16x32_bf16 v[84:87], v[204:207], v[220:223], v[84:87]
	v_mfma_f32_16x16x32_bf16 v[80:83], v[196:199], v[228:231], v[80:83]
	s_setprio 3
	s_barrier
; #define PG8_STAGE(bufoff, gbase, voff) do { _Pragma("unroll") for (int _i = 0; _i < 2; ++_i) \
;         __builtin_amdgcn_global_load_lds((const unsigned*)((const char*)(gbase) + (voff)[_i]), (PG8_LAS unsigned*)(lds + (bufoff) + ldsw + _i * 8192), 16, 0, 0); } while (0)
; #define PG8_LDA(dst, b, h) do { _Pragma("unroll") for (int m = 0; m < 4; ++m) _Pragma("unroll") for (int k = 0; k < 2; ++k) dst[m][k] = *(const PG8_LAS bf16x8*)(lds + PG8_SA(b, h) + aoff + m * 2048 + k * 1024); } while (0)
; #define PG8_MMA(ai, bj, At, Bt) do { __builtin_amdgcn_s_setprio(1); _Pragma("unroll") for (int m = 0; m < 4; ++m) _Pragma("unroll") for (int n = 0; n < 2; ++n) _Pragma("unroll") for (int k = 0; k < 2; ++k) \
;         acc[ai][bj][m][n] = __builtin_amdgcn_mfma_f32_16x16x32_bf16(Bt[n][k], At[m][k], acc[ai][bj][m][n], 0, 0, 0); __builtin_amdgcn_s_setprio(0); } while (0)
; #define PG8_WAIT_V(n) asm volatile("s_waitcnt vmcnt(" #n ")" ::: "memory")
; #define PG8_WAIT_L(n) asm volatile("s_waitcnt lgkmcnt(" #n ")" ::: "memory")
; #define PG8_BAR __builtin_amdgcn_s_barrier()
; #define PG8_SCHED __builtin_amdgcn_sched_barrier(0)
; template <class Epi, class Sched, bool ALIGN_EPI = false, bool SP2 = false>
; __device__ __forceinline__ void gemm_phase(PG8_LAS unsigned char* lds, const Gemm g, const Sched& S, const Epi& E) {
;     ...
;         for (int t = 0; t < nt; t += 2) {
;     ...
;             PG8_WAIT_V(8); PG8_WAIT_L(0); PG8_BAR; PG8_MMA(0, 0, At, B0); PG8_MMA(0, 1, At, B1); PG8_BAR; PG8_SCHED;
;             PG8_LDA(At, 1, 1); PG8_STAGE(PG8_SB(1, 0), b3, voffB); PG8_STAGE(PG8_SB(1, 1), b3 + hstep, voffB); PG8_STAGE(PG8_SA(1, 0), a3, voffA);
;             PG8_WAIT_V(8); PG8_WAIT_L(0); PG8_BAR; PG8_MMA(1, 0, At, B0); PG8_MMA(1, 1, At, B1); PG8_BAR; PG8_SCHED;
	v_mfma_f32_16x16x32_bf16 v[76:79], v[204:207], v[228:231], v[76:79]
	v_mfma_f32_16x16x32_bf16 v[72:75], v[196:199], v[248:251], v[72:75]
	v_mfma_f32_16x16x32_bf16 v[68:71], v[204:207], v[248:251], v[68:71]
	s_setprio 0
	s_add_i32 s22, s50, s30
	v_lshl_add_u64 v[6:7], v[156:157], 0, s[54:55]
	s_mov_b32 m0, s22
	ds_read_b128 v[208:211], v161 offset:49152
	ds_read_b128 v[212:215], v161 offset:50176
	ds_read_b128 v[216:219], v161 offset:51200
	ds_read_b128 v[220:223], v161 offset:52224
	ds_read_b128 v[224:227], v161 offset:53248
	ds_read_b128 v[228:231], v161 offset:54272
	ds_read_b128 v[244:247], v161 offset:55296
	ds_read_b128 v[248:251], v161 offset:56320
	global_load_lds_dwordx4 v[6:7], off
	s_add_i32 m0, s22, 0x2000
	s_add_u32 s20, s20, 0x20080
	v_lshl_add_u64 v[6:7], v[232:233], 0, s[54:55]
	s_addc_u32 s21, s21, 0
	s_add_i32 s22, s51, s30
	global_load_lds_dwordx4 v[6:7], off
	v_lshl_add_u64 v[6:7], s[20:21], 0, v[136:137]
	s_mov_b32 m0, s22
	s_nop 0
	global_load_lds_dwordx4 v[6:7], off
	v_lshl_add_u64 v[6:7], s[20:21], 0, v[132:133]
	s_add_i32 m0, s22, 0x2000
	s_nop 0
	global_load_lds_dwordx4 v[6:7], off
	v_lshl_add_u64 v[6:7], v[236:237], 0, s[54:55]
	s_mov_b32 m0, s41
	s_nop 0
	global_load_lds_dwordx4 v[6:7], off
	v_lshl_add_u64 v[6:7], v[252:253], 0, s[54:55]
	s_mov_b32 m0, s42
	s_nop 0
	global_load_lds_dwordx4 v[6:7], off
	s_waitcnt vmcnt(8)
	s_waitcnt lgkmcnt(0)
	s_barrier
	s_setprio 1
	s_waitcnt lgkmcnt(0)
	v_mfma_f32_16x16x32_bf16 v[64:67], v[144:147], v[208:211], v[64:67]
	v_mfma_f32_16x16x32_bf16 v[60:63], v[152:155], v[208:211], v[60:63]
	v_mfma_f32_16x16x32_bf16 v[56:59], v[144:147], v[216:219], v[56:59]
	v_mfma_f32_16x16x32_bf16 v[52:55], v[152:155], v[216:219], v[52:55]
	v_mfma_f32_16x16x32_bf16 v[48:51], v[144:147], v[224:227], v[48:51]
	v_mfma_f32_16x16x32_bf16 v[44:47], v[152:155], v[224:227], v[44:47]
	v_mfma_f32_16x16x32_bf16 v[40:43], v[144:147], v[244:247], v[40:43]
	v_mfma_f32_16x16x32_bf16 v[36:39], v[152:155], v[244:247], v[36:39]
	v_mfma_f32_16x16x32_bf16 v[64:67], v[148:151], v[212:215], v[64:67]
	v_mfma_f32_16x16x32_bf16 v[60:63], v[162:165], v[212:215], v[60:63]
	v_mfma_f32_16x16x32_bf16 v[56:59], v[148:151], v[220:223], v[56:59]
	v_mfma_f32_16x16x32_bf16 v[52:55], v[162:165], v[220:223], v[52:55]
	v_mfma_f32_16x16x32_bf16 v[48:51], v[148:151], v[228:231], v[48:51]
	v_mfma_f32_16x16x32_bf16 v[44:47], v[162:165], v[228:231], v[44:47]
	v_mfma_f32_16x16x32_bf16 v[40:43], v[148:151], v[248:251], v[40:43]
	v_mfma_f32_16x16x32_bf16 v[36:39], v[162:165], v[248:251], v[36:39]
	s_setprio 0
	s_setprio 1
	v_mfma_f32_16x16x32_bf16 v[32:35], v[192:195], v[208:211], v[32:35]
	v_mfma_f32_16x16x32_bf16 v[28:31], v[200:203], v[208:211], v[28:31]
	v_mfma_f32_16x16x32_bf16 v[24:27], v[192:195], v[216:219], v[24:27]
	v_mfma_f32_16x16x32_bf16 v[20:23], v[200:203], v[216:219], v[20:23]
	v_mfma_f32_16x16x32_bf16 v[16:19], v[192:195], v[224:227], v[16:19]
	v_mfma_f32_16x16x32_bf16 v[12:15], v[200:203], v[224:227], v[12:15]
	v_mfma_f32_16x16x32_bf16 v[6:9], v[192:195], v[244:247], v[8:11]
	v_mfma_f32_16x16x32_bf16 v[2:5], v[200:203], v[244:247], v[2:5]
	v_mfma_f32_16x16x32_bf16 v[32:35], v[196:199], v[212:215], v[32:35]
	v_mfma_f32_16x16x32_bf16 v[28:31], v[204:207], v[212:215], v[28:31]
	v_mfma_f32_16x16x32_bf16 v[24:27], v[196:199], v[220:223], v[24:27]
	v_mfma_f32_16x16x32_bf16 v[20:23], v[204:207], v[220:223], v[20:23]
	v_mfma_f32_16x16x32_bf16 v[16:19], v[196:199], v[228:231], v[16:19]
	s_setprio 3
	s_barrier
	v_mfma_f32_16x16x32_bf16 v[12:15], v[204:207], v[228:231], v[12:15]
	v_mfma_f32_16x16x32_bf16 v[8:11], v[196:199], v[248:251], v[6:9]
	v_mfma_f32_16x16x32_bf16 v[4:7], v[204:207], v[248:251], v[2:5]
	s_setprio 0
	s_add_i32 s49, s49, 2
	s_add_u32 s47, s47, 0x100
	s_addc_u32 s48, s48, 0
	s_add_u32 s6, s6, 0x100
	s_addc_u32 s7, s7, 0
	s_cmp_gt_u32 s49, 5
	s_cbranch_scc0 .LBB0_514
	s_and_b64 vcc, exec, s[4:5]
	s_cbranch_vccz .LBB0_517
	s_barrier

; #define PG8_STAGE(bufoff, gbase, voff) do { _Pragma("unroll") for (int _i = 0; _i < 2; ++_i) \
;         __builtin_amdgcn_global_load_lds((const unsigned*)((const char*)(gbase) + (voff)[_i]), (PG8_LAS unsigned*)(lds + (bufoff) + ldsw + _i * 8192), 16, 0, 0); } while (0)
; #define PG8_LDA(dst, b, h) do { _Pragma("unroll") for (int m = 0; m < 4; ++m) _Pragma("unroll") for (int k = 0; k < 2; ++k) dst[m][k] = *(const PG8_LAS bf16x8*)(lds + PG8_SA(b, h) + aoff + m * 2048 + k * 1024); } while (0)
; #define PG8_LDB(dst, b, h) do { _Pragma("unroll") for (int n = 0; n < 2; ++n) _Pragma("unroll") for (int k = 0; k < 2; ++k) dst[n][k] = *(const PG8_LAS bf16x8*)(lds + PG8_SB(b, h) + boff + n * 2048 + k * 1024); } while (0)
; #define PG8_MMA(ai, bj, At, Bt) do { __builtin_amdgcn_s_setprio(1); _Pragma("unroll") for (int m = 0; m < 4; ++m) _Pragma("unroll") for (int n = 0; n < 2; ++n) _Pragma("unroll") for (int k = 0; k < 2; ++k) \
;         acc[ai][bj][m][n] = __builtin_amdgcn_mfma_f32_16x16x32_bf16(Bt[n][k], At[m][k], acc[ai][bj][m][n], 0, 0, 0); __builtin_amdgcn_s_setprio(0); } while (0)
; #define PG8_WAIT_V(n) asm volatile("s_waitcnt vmcnt(" #n ")" ::: "memory")
; #define PG8_WAIT_L(n) asm volatile("s_waitcnt lgkmcnt(" #n ")" ::: "memory")
; template <class Epi, class Sched, bool ALIGN_EPI = false, bool SP2 = false>
; __device__ __forceinline__ void gemm_phase(PG8_LAS unsigned char* lds, const Gemm g, const Sched& S, const Epi& E) {
;     ...
;             const bool last = (t == nt - 2);
;             const char* a1 = cA + (size_t)(t + 1) * kstep;
;             const char* a2 = last ? nA : cA + (size_t)(t + 2) * kstep; const char* b2 = last ? nB : cB + (size_t)(t + 2) * kstep;
;             const char* a3 = a2 + kstep; const char* b3 = b2 + kstep;
;             if (last && has_next) S.a_ready(nxt);
;             if constexpr (SP2) {
;             PG8_LDB(B0, 0, 0); PG8_LDB(B1, 0, 1); PG8_SCHED; PG8_LDA(At, 0, 0); PG8_STAGE(PG8_SA(1, 1), a1 + hstep, voffA);
;             PG8_WAIT_V(8); PG8_WAIT_L(0); PG8_BAR; PG8_MMA(0, 0, At, B0); PG8_MMA(0, 1, At, B1); PG8_BAR; PG8_SCHED;
;             PG8_LDA(At, 0, 1); PG8_STAGE(PG8_SB(0, 0), b2, voffB); PG8_STAGE(PG8_SB(0, 1), b2 + hstep, voffB); PG8_STAGE(PG8_SA(0, 0), a2, voffA);
;             PG8_WAIT_V(8); PG8_WAIT_L(0); PG8_BAR; PG8_MMA(1, 0, At, B0); PG8_MMA(1, 1, At, B1); PG8_BAR; PG8_SCHED;
.LBB0_663:
	s_add_u32 s26, s24, 0xfffc0080
	s_addc_u32 s27, s25, -1
	s_add_i32 s51, 0, 0x10000
	s_cmp_eq_u32 s50, 12
	s_cselect_b32 s29, s15, s27
	s_cselect_b32 s28, s21, s26
	v_add_u32_e32 v144, s51, v147
	s_cselect_b32 s27, s13, s49
	s_cselect_b32 s26, s23, s48
	s_add_i32 s54, 0, 0x14000
	ds_read_b128 v[140:143], v144
	ds_read_b128 v[150:153], v144 offset:1024
	ds_read_b128 v[154:157], v144 offset:2048
	ds_read_b128 v[158:161], v144 offset:3072
	v_add_u32_e32 v144, s54, v147
	ds_read_b128 v[162:165], v144
	ds_read_b128 v[192:195], v144 offset:1024
	ds_read_b128 v[196:199], v144 offset:2048
	ds_read_b128 v[200:203], v144 offset:3072
	v_lshl_add_u64 v[144:145], s[24:25], 0, v[138:139]
	s_add_i32 m0, s38, 0xc000
	ds_read_b128 v[204:207], v149
	ds_read_b128 v[208:211], v149 offset:1024
	ds_read_b128 v[212:215], v149 offset:2048
	ds_read_b128 v[216:219], v149 offset:3072
	ds_read_b128 v[220:223], v149 offset:4096
	ds_read_b128 v[224:227], v149 offset:5120
	ds_read_b128 v[228:231], v149 offset:6144
	ds_read_b128 v[244:247], v149 offset:7168
	global_load_lds_dwordx4 v[144:145], off
	v_lshl_add_u64 v[144:145], s[24:25], 0, v[136:137]
	s_add_i32 m0, s38, 0xe000
	s_nop 0
	global_load_lds_dwordx4 v[144:145], off
	s_waitcnt vmcnt(8)
	s_waitcnt lgkmcnt(0)
	s_barrier
	s_setprio 1
	s_waitcnt lgkmcnt(0)
	v_mfma_f32_16x16x32_bf16 v[126:129], v[140:143], v[204:207], v[126:129]
	v_mfma_f32_16x16x32_bf16 v[122:125], v[154:157], v[204:207], v[122:125]
	v_mfma_f32_16x16x32_bf16 v[110:113], v[140:143], v[212:215], v[110:113]
	v_mfma_f32_16x16x32_bf16 v[106:109], v[154:157], v[212:215], v[106:109]
	v_mfma_f32_16x16x32_bf16 v[94:97], v[140:143], v[220:223], v[94:97]
	v_mfma_f32_16x16x32_bf16 v[90:93], v[154:157], v[220:223], v[90:93]
	v_mfma_f32_16x16x32_bf16 v[78:81], v[140:143], v[228:231], v[78:81]
	v_mfma_f32_16x16x32_bf16 v[74:77], v[154:157], v[228:231], v[74:77]
	v_mfma_f32_16x16x32_bf16 v[126:129], v[150:153], v[208:211], v[126:129]
	v_mfma_f32_16x16x32_bf16 v[122:125], v[158:161], v[208:211], v[122:125]
	v_mfma_f32_16x16x32_bf16 v[110:113], v[150:153], v[216:219], v[110:113]
	v_mfma_f32_16x16x32_bf16 v[106:109], v[158:161], v[216:219], v[106:109]
	v_mfma_f32_16x16x32_bf16 v[94:97], v[150:153], v[224:227], v[94:97]
	v_mfma_f32_16x16x32_bf16 v[90:93], v[158:161], v[224:227], v[90:93]
	v_mfma_f32_16x16x32_bf16 v[78:81], v[150:153], v[244:247], v[78:81]
	v_mfma_f32_16x16x32_bf16 v[74:77], v[158:161], v[244:247], v[74:77]
	s_setprio 0
	s_setprio 1
	v_mfma_f32_16x16x32_bf16 v[118:121], v[162:165], v[204:207], v[118:121]
	v_mfma_f32_16x16x32_bf16 v[114:117], v[196:199], v[204:207], v[114:117]
	v_mfma_f32_16x16x32_bf16 v[102:105], v[162:165], v[212:215], v[102:105]
	v_mfma_f32_16x16x32_bf16 v[98:101], v[196:199], v[212:215], v[98:101]
	v_mfma_f32_16x16x32_bf16 v[86:89], v[162:165], v[220:223], v[86:89]
	v_mfma_f32_16x16x32_bf16 v[82:85], v[196:199], v[220:223], v[82:85]
	v_mfma_f32_16x16x32_bf16 v[70:73], v[162:165], v[228:231], v[70:73]
	v_mfma_f32_16x16x32_bf16 v[66:69], v[196:199], v[228:231], v[66:69]
	v_mfma_f32_16x16x32_bf16 v[118:121], v[192:195], v[208:211], v[118:121]
	v_mfma_f32_16x16x32_bf16 v[114:117], v[200:203], v[208:211], v[114:117]
	v_mfma_f32_16x16x32_bf16 v[102:105], v[192:195], v[216:219], v[102:105]
	v_mfma_f32_16x16x32_bf16 v[98:101], v[200:203], v[216:219], v[98:101]
	v_mfma_f32_16x16x32_bf16 v[86:89], v[192:195], v[224:227], v[86:89]
	s_setprio 3
	s_barrier
	v_mfma_f32_16x16x32_bf16 v[82:85], v[200:203], v[224:227], v[82:85]
	v_mfma_f32_16x16x32_bf16 v[70:73], v[192:195], v[244:247], v[70:73]
	v_mfma_f32_16x16x32_bf16 v[66:69], v[200:203], v[244:247], v[66:69]
	s_setprio 0
	s_add_i32 s51, s51, s37
	v_lshl_add_u64 v[144:145], s[26:27], 0, v[0:1]
	s_mov_b32 m0, s51
	ds_read_b128 v[204:207], v149 offset:16384
	ds_read_b128 v[208:211], v149 offset:17408
	ds_read_b128 v[212:215], v149 offset:18432
	ds_read_b128 v[216:219], v149 offset:19456
	ds_read_b128 v[220:223], v149 offset:20480
	ds_read_b128 v[224:227], v149 offset:21504
	ds_read_b128 v[228:231], v149 offset:22528
	ds_read_b128 v[244:247], v149 offset:23552
	global_load_lds_dwordx4 v[144:145], off
	s_add_i32 m0, s51, 0x2000
	s_add_u32 s52, s26, 0x40000
	v_lshl_add_u64 v[232:233], s[26:27], 0, v[134:135]
	s_addc_u32 s53, s27, 0
	s_add_i32 s51, s54, s37
	global_load_lds_dwordx4 v[232:233], off
	v_lshl_add_u64 v[236:237], s[52:53], 0, v[0:1]
	s_mov_b32 m0, s51
	v_lshl_add_u64 v[248:249], s[28:29], 0, v[132:133]
	global_load_lds_dwordx4 v[236:237], off
	v_lshl_add_u64 v[236:237], s[52:53], 0, v[134:135]
	s_add_i32 m0, s51, 0x2000
	s_nop 0
	global_load_lds_dwordx4 v[236:237], off
	v_lshl_add_u64 v[236:237], s[28:29], 0, v[130:131]
	s_mov_b32 m0, s38
	s_nop 0
	global_load_lds_dwordx4 v[236:237], off
	s_mov_b32 m0, s39
	s_nop 0
	global_load_lds_dwordx4 v[248:249], off
	s_waitcnt vmcnt(8)
	s_waitcnt lgkmcnt(0)
	s_barrier
; #define PG8_STAGE(bufoff, gbase, voff) do { _Pragma("unroll") for (int _i = 0; _i < 2; ++_i) \
;         __builtin_amdgcn_global_load_lds((const unsigned*)((const char*)(gbase) + (voff)[_i]), (PG8_LAS unsigned*)(lds + (bufoff) + ldsw + _i * 8192), 16, 0, 0); } while (0)
; #define PG8_LDA(dst, b, h) do { _Pragma("unroll") for (int m = 0; m < 4; ++m) _Pragma("unroll") for (int k = 0; k < 2; ++k) dst[m][k] = *(const PG8_LAS bf16x8*)(lds + PG8_SA(b, h) + aoff + m * 2048 + k * 1024); } while (0)
; #define PG8_LDB(dst, b, h) do { _Pragma("unroll") for (int n = 0; n < 2; ++n) _Pragma("unroll") for (int k = 0; k < 2; ++k) dst[n][k] = *(const PG8_LAS bf16x8*)(lds + PG8_SB(b, h) + boff + n * 2048 + k * 1024); } while (0)
; #define PG8_MMA(ai, bj, At, Bt) do { __builtin_amdgcn_s_setprio(1); _Pragma("unroll") for (int m = 0; m < 4; ++m) _Pragma("unroll") for (int n = 0; n < 2; ++n) _Pragma("unroll") for (int k = 0; k < 2; ++k) \
;         acc[ai][bj][m][n] = __builtin_amdgcn_mfma_f32_16x16x32_bf16(Bt[n][k], At[m][k], acc[ai][bj][m][n], 0, 0, 0); __builtin_amdgcn_s_setprio(0); } while (0)
; #define PG8_WAIT_V(n) asm volatile("s_waitcnt vmcnt(" #n ")" ::: "memory")
; #define PG8_WAIT_L(n) asm volatile("s_waitcnt lgkmcnt(" #n ")" ::: "memory")
; #define PG8_BAR __builtin_amdgcn_s_barrier()
; #define PG8_SCHED __builtin_amdgcn_sched_barrier(0)
; template <class Epi, class Sched, bool ALIGN_EPI = false, bool SP2 = false>
; __device__ __forceinline__ void gemm_phase(PG8_LAS unsigned char* lds, const Gemm g, const Sched& S, const Epi& E) {
;     ...
;             PG8_WAIT_V(8); PG8_WAIT_L(0); PG8_BAR; PG8_MMA(1, 0, At, B0); PG8_MMA(1, 1, At, B1); PG8_BAR; PG8_SCHED;
;             PG8_LDB(B0, 1, 0); PG8_LDB(B1, 1, 1); PG8_SCHED; PG8_LDA(At, 1, 0); PG8_STAGE(PG8_SA(0, 1), a2 + hstep, voffA);
;             PG8_WAIT_V(8); PG8_WAIT_L(0); PG8_BAR; PG8_MMA(0, 0, At, B0); PG8_MMA(0, 1, At, B1); PG8_BAR; PG8_SCHED;
	s_setprio 1
	s_waitcnt lgkmcnt(0)
	v_mfma_f32_16x16x32_bf16 v[62:65], v[140:143], v[204:207], v[62:65]
	v_mfma_f32_16x16x32_bf16 v[58:61], v[154:157], v[204:207], v[58:61]
	v_mfma_f32_16x16x32_bf16 v[46:49], v[140:143], v[212:215], v[46:49]
	v_mfma_f32_16x16x32_bf16 v[42:45], v[154:157], v[212:215], v[42:45]
	v_mfma_f32_16x16x32_bf16 v[30:33], v[140:143], v[220:223], v[30:33]
	v_mfma_f32_16x16x32_bf16 v[26:29], v[154:157], v[220:223], v[26:29]
	v_mfma_f32_16x16x32_bf16 v[14:17], v[140:143], v[228:231], v[14:17]
	v_mfma_f32_16x16x32_bf16 v[10:13], v[154:157], v[228:231], v[10:13]
	v_mfma_f32_16x16x32_bf16 v[62:65], v[150:153], v[208:211], v[62:65]
	v_mfma_f32_16x16x32_bf16 v[58:61], v[158:161], v[208:211], v[58:61]
	v_mfma_f32_16x16x32_bf16 v[46:49], v[150:153], v[216:219], v[46:49]
	v_mfma_f32_16x16x32_bf16 v[42:45], v[158:161], v[216:219], v[42:45]
	v_mfma_f32_16x16x32_bf16 v[30:33], v[150:153], v[224:227], v[30:33]
	v_mfma_f32_16x16x32_bf16 v[26:29], v[158:161], v[224:227], v[26:29]
	v_mfma_f32_16x16x32_bf16 v[14:17], v[150:153], v[244:247], v[14:17]
	v_mfma_f32_16x16x32_bf16 v[10:13], v[158:161], v[244:247], v[10:13]
	s_setprio 0
	s_setprio 1
	v_mfma_f32_16x16x32_bf16 v[54:57], v[162:165], v[204:207], v[54:57]
	v_mfma_f32_16x16x32_bf16 v[50:53], v[196:199], v[204:207], v[50:53]
	v_mfma_f32_16x16x32_bf16 v[38:41], v[162:165], v[212:215], v[38:41]
	v_mfma_f32_16x16x32_bf16 v[34:37], v[196:199], v[212:215], v[34:37]
	v_mfma_f32_16x16x32_bf16 v[22:25], v[162:165], v[220:223], v[22:25]
	v_mfma_f32_16x16x32_bf16 v[18:21], v[196:199], v[220:223], v[18:21]
	v_mfma_f32_16x16x32_bf16 v[6:9], v[162:165], v[228:231], v[6:9]
	v_mfma_f32_16x16x32_bf16 v[2:5], v[196:199], v[228:231], v[2:5]
	v_mfma_f32_16x16x32_bf16 v[54:57], v[192:195], v[208:211], v[54:57]
	v_mfma_f32_16x16x32_bf16 v[50:53], v[200:203], v[208:211], v[50:53]
	v_mfma_f32_16x16x32_bf16 v[38:41], v[192:195], v[216:219], v[38:41]
	v_mfma_f32_16x16x32_bf16 v[34:37], v[200:203], v[216:219], v[34:37]
	v_mfma_f32_16x16x32_bf16 v[22:25], v[192:195], v[224:227], v[22:25]
	s_setprio 3
	s_barrier
	v_mfma_f32_16x16x32_bf16 v[18:21], v[200:203], v[224:227], v[18:21]
	v_mfma_f32_16x16x32_bf16 v[6:9], v[192:195], v[244:247], v[6:9]
	v_mfma_f32_16x16x32_bf16 v[2:5], v[200:203], v[244:247], v[2:5]
	s_setprio 0
	s_add_i32 s51, 0, 0x18000
	s_add_i32 s52, 0, 0x1c000
	v_add_u32_e32 v158, s51, v147
	v_add_u32_e32 v182, s52, v147
	ds_read_b128 v[140:143], v158
	ds_read_b128 v[150:153], v158 offset:1024
	ds_read_b128 v[154:157], v158 offset:2048
	ds_read_b128 v[158:161], v158 offset:3072
	ds_read_b128 v[162:165], v182
	ds_read_b128 v[192:195], v182 offset:1024
	ds_read_b128 v[196:199], v182 offset:2048
	ds_read_b128 v[200:203], v182 offset:3072
	s_add_u32 s28, s28, 0x40000
	s_addc_u32 s29, s29, 0
	s_mov_b32 m0, s40
	v_lshl_add_u64 v[250:251], s[28:29], 0, v[130:131]
	ds_read_b128 v[204:207], v149 offset:32768
	ds_read_b128 v[208:211], v149 offset:33792
	ds_read_b128 v[212:215], v149 offset:34816
	ds_read_b128 v[216:219], v149 offset:35840
	ds_read_b128 v[220:223], v149 offset:36864
	ds_read_b128 v[224:227], v149 offset:37888
	ds_read_b128 v[228:231], v149 offset:38912
	ds_read_b128 v[244:247], v149 offset:39936
	global_load_lds_dwordx4 v[250:251], off
	v_lshl_add_u64 v[250:251], s[28:29], 0, v[132:133]
	s_mov_b32 m0, s41
	s_nop 0
	global_load_lds_dwordx4 v[250:251], off
	s_waitcnt vmcnt(8)
	s_waitcnt lgkmcnt(0)
	s_barrier
	s_setprio 1
	s_waitcnt lgkmcnt(0)
	v_mfma_f32_16x16x32_bf16 v[126:129], v[140:143], v[204:207], v[126:129]
	v_mfma_f32_16x16x32_bf16 v[122:125], v[154:157], v[204:207], v[122:125]
	v_mfma_f32_16x16x32_bf16 v[110:113], v[140:143], v[212:215], v[110:113]
	v_mfma_f32_16x16x32_bf16 v[106:109], v[154:157], v[212:215], v[106:109]
	v_mfma_f32_16x16x32_bf16 v[94:97], v[140:143], v[220:223], v[94:97]
	v_mfma_f32_16x16x32_bf16 v[90:93], v[154:157], v[220:223], v[90:93]
	v_mfma_f32_16x16x32_bf16 v[78:81], v[140:143], v[228:231], v[78:81]
	v_mfma_f32_16x16x32_bf16 v[74:77], v[154:157], v[228:231], v[74:77]
	v_mfma_f32_16x16x32_bf16 v[126:129], v[150:153], v[208:211], v[126:129]
	v_mfma_f32_16x16x32_bf16 v[122:125], v[158:161], v[208:211], v[122:125]
	v_mfma_f32_16x16x32_bf16 v[110:113], v[150:153], v[216:219], v[110:113]
	v_mfma_f32_16x16x32_bf16 v[106:109], v[158:161], v[216:219], v[106:109]
	v_mfma_f32_16x16x32_bf16 v[94:97], v[150:153], v[224:227], v[94:97]
	v_mfma_f32_16x16x32_bf16 v[90:93], v[158:161], v[224:227], v[90:93]
	v_mfma_f32_16x16x32_bf16 v[78:81], v[150:153], v[244:247], v[78:81]
	v_mfma_f32_16x16x32_bf16 v[74:77], v[158:161], v[244:247], v[74:77]
	s_setprio 0
	s_setprio 1
	v_mfma_f32_16x16x32_bf16 v[118:121], v[162:165], v[204:207], v[118:121]
	v_mfma_f32_16x16x32_bf16 v[114:117], v[196:199], v[204:207], v[114:117]
	v_mfma_f32_16x16x32_bf16 v[102:105], v[162:165], v[212:215], v[102:105]
	v_mfma_f32_16x16x32_bf16 v[98:101], v[196:199], v[212:215], v[98:101]
	v_mfma_f32_16x16x32_bf16 v[86:89], v[162:165], v[220:223], v[86:89]
	v_mfma_f32_16x16x32_bf16 v[82:85], v[196:199], v[220:223], v[82:85]
	v_mfma_f32_16x16x32_bf16 v[70:73], v[162:165], v[228:231], v[70:73]
	v_mfma_f32_16x16x32_bf16 v[66:69], v[196:199], v[228:231], v[66:69]
	v_mfma_f32_16x16x32_bf16 v[118:121], v[192:195], v[208:211], v[118:121]
	v_mfma_f32_16x16x32_bf16 v[114:117], v[200:203], v[208:211], v[114:117]
	v_mfma_f32_16x16x32_bf16 v[102:105], v[192:195], v[216:219], v[102:105]
	v_mfma_f32_16x16x32_bf16 v[98:101], v[200:203], v[216:219], v[98:101]
	v_mfma_f32_16x16x32_bf16 v[86:89], v[192:195], v[224:227], v[86:89]
	s_setprio 3
	s_barrier
; #define PG8_STAGE(bufoff, gbase, voff) do { _Pragma("unroll") for (int _i = 0; _i < 2; ++_i) \
;         __builtin_amdgcn_global_load_lds((const unsigned*)((const char*)(gbase) + (voff)[_i]), (PG8_LAS unsigned*)(lds + (bufoff) + ldsw + _i * 8192), 16, 0, 0); } while (0)
; #define PG8_LDA(dst, b, h) do { _Pragma("unroll") for (int m = 0; m < 4; ++m) _Pragma("unroll") for (int k = 0; k < 2; ++k) dst[m][k] = *(const PG8_LAS bf16x8*)(lds + PG8_SA(b, h) + aoff + m * 2048 + k * 1024); } while (0)
; #define PG8_MMA(ai, bj, At, Bt) do { __builtin_amdgcn_s_setprio(1); _Pragma("unroll") for (int m = 0; m < 4; ++m) _Pragma("unroll") for (int n = 0; n < 2; ++n) _Pragma("unroll") for (int k = 0; k < 2; ++k) \
;         acc[ai][bj][m][n] = __builtin_amdgcn_mfma_f32_16x16x32_bf16(Bt[n][k], At[m][k], acc[ai][bj][m][n], 0, 0, 0); __builtin_amdgcn_s_setprio(0); } while (0)
; #define PG8_WAIT_V(n) asm volatile("s_waitcnt vmcnt(" #n ")" ::: "memory")
; #define PG8_WAIT_L(n) asm volatile("s_waitcnt lgkmcnt(" #n ")" ::: "memory")
; #define PG8_BAR __builtin_amdgcn_s_barrier()
; #define PG8_SCHED __builtin_amdgcn_sched_barrier(0)
; template <class Epi, class Sched, bool ALIGN_EPI = false, bool SP2 = false>
; __device__ __forceinline__ void gemm_phase(PG8_LAS unsigned char* lds, const Gemm g, const Sched& S, const Epi& E) {
;     ...
;         for (int t = 0; t < nt; t += 2) {
;     ...
;             PG8_WAIT_V(8); PG8_WAIT_L(0); PG8_BAR; PG8_MMA(0, 0, At, B0); PG8_MMA(0, 1, At, B1); PG8_BAR; PG8_SCHED;
;             PG8_LDA(At, 1, 1); PG8_STAGE(PG8_SB(1, 0), b3, voffB); PG8_STAGE(PG8_SB(1, 1), b3 + hstep, voffB); PG8_STAGE(PG8_SA(1, 0), a3, voffA);
;             PG8_WAIT_V(8); PG8_WAIT_L(0); PG8_BAR; PG8_MMA(1, 0, At, B0); PG8_MMA(1, 1, At, B1); PG8_BAR; PG8_SCHED;
	v_mfma_f32_16x16x32_bf16 v[82:85], v[200:203], v[224:227], v[82:85]
	v_mfma_f32_16x16x32_bf16 v[70:73], v[192:195], v[244:247], v[70:73]
	v_mfma_f32_16x16x32_bf16 v[66:69], v[200:203], v[244:247], v[66:69]
	s_setprio 0
	s_add_i32 s28, s51, s37
	v_lshl_add_u64 v[144:145], v[144:145], 0, s[56:57]
	s_mov_b32 m0, s28
	ds_read_b128 v[204:207], v149 offset:49152
	ds_read_b128 v[208:211], v149 offset:50176
	ds_read_b128 v[212:215], v149 offset:51200
	ds_read_b128 v[216:219], v149 offset:52224
	ds_read_b128 v[220:223], v149 offset:53248
	ds_read_b128 v[224:227], v149 offset:54272
	ds_read_b128 v[228:231], v149 offset:55296
	ds_read_b128 v[244:247], v149 offset:56320
	global_load_lds_dwordx4 v[144:145], off
	s_add_i32 m0, s28, 0x2000
	s_add_u32 s26, s26, 0x40080
	v_lshl_add_u64 v[144:145], v[232:233], 0, s[56:57]
	s_addc_u32 s27, s27, 0
	s_add_i32 s28, s52, s37
	global_load_lds_dwordx4 v[144:145], off
	v_lshl_add_u64 v[144:145], s[26:27], 0, v[0:1]
	s_mov_b32 m0, s28
	s_nop 0
	global_load_lds_dwordx4 v[144:145], off
	v_lshl_add_u64 v[144:145], s[26:27], 0, v[134:135]
	s_add_i32 m0, s28, 0x2000
	s_nop 0
	global_load_lds_dwordx4 v[144:145], off
	v_lshl_add_u64 v[144:145], v[236:237], 0, s[56:57]
	s_mov_b32 m0, s43
	s_nop 0
	global_load_lds_dwordx4 v[144:145], off
	v_lshl_add_u64 v[144:145], v[248:249], 0, s[56:57]
	s_mov_b32 m0, s44
	s_nop 0
	global_load_lds_dwordx4 v[144:145], off
	s_waitcnt vmcnt(8)
	s_waitcnt lgkmcnt(0)
	s_barrier
	s_setprio 1
	s_waitcnt lgkmcnt(0)
	v_mfma_f32_16x16x32_bf16 v[62:65], v[140:143], v[204:207], v[62:65]
	v_mfma_f32_16x16x32_bf16 v[58:61], v[154:157], v[204:207], v[58:61]
	v_mfma_f32_16x16x32_bf16 v[46:49], v[140:143], v[212:215], v[46:49]
	v_mfma_f32_16x16x32_bf16 v[42:45], v[154:157], v[212:215], v[42:45]
	v_mfma_f32_16x16x32_bf16 v[30:33], v[140:143], v[220:223], v[30:33]
	v_mfma_f32_16x16x32_bf16 v[26:29], v[154:157], v[220:223], v[26:29]
	v_mfma_f32_16x16x32_bf16 v[14:17], v[140:143], v[228:231], v[14:17]
	v_mfma_f32_16x16x32_bf16 v[10:13], v[154:157], v[228:231], v[10:13]
	v_mfma_f32_16x16x32_bf16 v[62:65], v[150:153], v[208:211], v[62:65]
	v_mfma_f32_16x16x32_bf16 v[58:61], v[158:161], v[208:211], v[58:61]
	v_mfma_f32_16x16x32_bf16 v[46:49], v[150:153], v[216:219], v[46:49]
	v_mfma_f32_16x16x32_bf16 v[42:45], v[158:161], v[216:219], v[42:45]
	v_mfma_f32_16x16x32_bf16 v[30:33], v[150:153], v[224:227], v[30:33]
	v_mfma_f32_16x16x32_bf16 v[26:29], v[158:161], v[224:227], v[26:29]
	v_mfma_f32_16x16x32_bf16 v[14:17], v[150:153], v[244:247], v[14:17]
	v_mfma_f32_16x16x32_bf16 v[10:13], v[158:161], v[244:247], v[10:13]
	s_setprio 0
	s_setprio 1
	v_mfma_f32_16x16x32_bf16 v[54:57], v[162:165], v[204:207], v[54:57]
	v_mfma_f32_16x16x32_bf16 v[50:53], v[196:199], v[204:207], v[50:53]
	v_mfma_f32_16x16x32_bf16 v[38:41], v[162:165], v[212:215], v[38:41]
	v_mfma_f32_16x16x32_bf16 v[34:37], v[196:199], v[212:215], v[34:37]
	v_mfma_f32_16x16x32_bf16 v[22:25], v[162:165], v[220:223], v[22:25]
	v_mfma_f32_16x16x32_bf16 v[18:21], v[196:199], v[220:223], v[18:21]
	v_mfma_f32_16x16x32_bf16 v[6:9], v[162:165], v[228:231], v[6:9]
	v_mfma_f32_16x16x32_bf16 v[2:5], v[196:199], v[228:231], v[2:5]
	v_mfma_f32_16x16x32_bf16 v[54:57], v[192:195], v[208:211], v[54:57]
	v_mfma_f32_16x16x32_bf16 v[50:53], v[200:203], v[208:211], v[50:53]
	v_mfma_f32_16x16x32_bf16 v[38:41], v[192:195], v[216:219], v[38:41]
	v_mfma_f32_16x16x32_bf16 v[34:37], v[200:203], v[216:219], v[34:37]
	v_mfma_f32_16x16x32_bf16 v[22:25], v[192:195], v[224:227], v[22:25]
	s_setprio 3
	s_barrier
	v_mfma_f32_16x16x32_bf16 v[18:21], v[200:203], v[224:227], v[18:21]
	v_mfma_f32_16x16x32_bf16 v[6:9], v[192:195], v[244:247], v[6:9]
	v_mfma_f32_16x16x32_bf16 v[2:5], v[200:203], v[244:247], v[2:5]
	s_setprio 0
	s_add_i32 s50, s50, 2
	s_add_u32 s48, s48, 0x100
	s_addc_u32 s49, s49, 0
	s_add_u32 s24, s24, 0x100
	s_addc_u32 s25, s25, 0
	s_cmp_gt_u32 s50, 13
	s_cbranch_scc0 .LBB0_663
	s_and_b64 vcc, exec, s[10:11]
	s_cbranch_vccz .LBB0_666
	s_barrier

; #define PG8_STAGE(bufoff, gbase, voff) do { _Pragma("unroll") for (int _i = 0; _i < 2; ++_i) \
;         __builtin_amdgcn_global_load_lds((const unsigned*)((const char*)(gbase) + (voff)[_i]), (PG8_LAS unsigned*)(lds + (bufoff) + ldsw + _i * 8192), 16, 0, 0); } while (0)
; #define PG8_LDA(dst, b, h) do { _Pragma("unroll") for (int m = 0; m < 4; ++m) _Pragma("unroll") for (int k = 0; k < 2; ++k) dst[m][k] = *(const PG8_LAS bf16x8*)(lds + PG8_SA(b, h) + aoff + m * 2048 + k * 1024); } while (0)
; #define PG8_LDB(dst, b, h) do { _Pragma("unroll") for (int n = 0; n < 2; ++n) _Pragma("unroll") for (int k = 0; k < 2; ++k) dst[n][k] = *(const PG8_LAS bf16x8*)(lds + PG8_SB(b, h) + boff + n * 2048 + k * 1024); } while (0)
; #define PG8_MMA(ai, bj, At, Bt) do { __builtin_amdgcn_s_setprio(1); _Pragma("unroll") for (int m = 0; m < 4; ++m) _Pragma("unroll") for (int n = 0; n < 2; ++n) _Pragma("unroll") for (int k = 0; k < 2; ++k) \
;         acc[ai][bj][m][n] = __builtin_amdgcn_mfma_f32_16x16x32_bf16(Bt[n][k], At[m][k], acc[ai][bj][m][n], 0, 0, 0); __builtin_amdgcn_s_setprio(0); } while (0)
; #define PG8_WAIT_V(n) asm volatile("s_waitcnt vmcnt(" #n ")" ::: "memory")
; #define PG8_WAIT_L(n) asm volatile("s_waitcnt lgkmcnt(" #n ")" ::: "memory")
; template <class Epi, class Sched, bool ALIGN_EPI = false, bool SP2 = false>
; __device__ __forceinline__ void gemm_phase(PG8_LAS unsigned char* lds, const Gemm g, const Sched& S, const Epi& E) {
;     ...
;             const bool last = (t == nt - 2);
;             const char* a1 = cA + (size_t)(t + 1) * kstep;
;             const char* a2 = last ? nA : cA + (size_t)(t + 2) * kstep; const char* b2 = last ? nB : cB + (size_t)(t + 2) * kstep;
;             const char* a3 = a2 + kstep; const char* b3 = b2 + kstep;
;             if (last && has_next) S.a_ready(nxt);
;             if constexpr (SP2) {
;             PG8_LDB(B0, 0, 0); PG8_LDB(B1, 0, 1); PG8_SCHED; PG8_LDA(At, 0, 0); PG8_STAGE(PG8_SA(1, 1), a1 + hstep, voffA);
;             PG8_WAIT_V(8); PG8_WAIT_L(0); PG8_BAR; PG8_MMA(0, 0, At, B0); PG8_MMA(0, 1, At, B1); PG8_BAR; PG8_SCHED;
;             PG8_LDA(At, 0, 1); PG8_STAGE(PG8_SB(0, 0), b2, voffB); PG8_STAGE(PG8_SB(0, 1), b2 + hstep, voffB); PG8_STAGE(PG8_SA(0, 0), a2, voffA);
;             PG8_WAIT_V(8); PG8_WAIT_L(0); PG8_BAR; PG8_MMA(1, 0, At, B0); PG8_MMA(1, 1, At, B1); PG8_BAR; PG8_SCHED;
.LBB0_752:
	s_add_u32 s22, s20, 0xfffc0080
	s_addc_u32 s23, s21, -1
	s_add_i32 s48, 0, 0x10000
	s_cmp_eq_u32 s47, 12
	s_cselect_b32 s25, s13, s23
	s_cselect_b32 s24, s43, s22
	v_add_u32_e32 v144, s48, v147
	s_cselect_b32 s23, s11, s46
	s_cselect_b32 s22, s44, s45
	s_add_i32 s50, 0, 0x14000
	ds_read_b128 v[140:143], v144
	ds_read_b128 v[150:153], v144 offset:1024
	ds_read_b128 v[154:157], v144 offset:2048
	ds_read_b128 v[158:161], v144 offset:3072
	v_add_u32_e32 v144, s50, v147
	ds_read_b128 v[162:165], v144
	ds_read_b128 v[192:195], v144 offset:1024
	ds_read_b128 v[196:199], v144 offset:2048
	ds_read_b128 v[200:203], v144 offset:3072
	v_lshl_add_u64 v[144:145], s[20:21], 0, v[138:139]
	s_add_i32 m0, s35, 0xc000
	ds_read_b128 v[204:207], v149
	ds_read_b128 v[208:211], v149 offset:1024
	ds_read_b128 v[212:215], v149 offset:2048
	ds_read_b128 v[216:219], v149 offset:3072
	ds_read_b128 v[220:223], v149 offset:4096
	ds_read_b128 v[224:227], v149 offset:5120
	ds_read_b128 v[228:231], v149 offset:6144
	ds_read_b128 v[244:247], v149 offset:7168
	global_load_lds_dwordx4 v[144:145], off
	v_lshl_add_u64 v[144:145], s[20:21], 0, v[136:137]
	s_add_i32 m0, s35, 0xe000
	s_nop 0
	global_load_lds_dwordx4 v[144:145], off
	s_waitcnt vmcnt(8)
	s_waitcnt lgkmcnt(0)
	s_barrier
	s_setprio 1
	s_waitcnt lgkmcnt(0)
	v_mfma_f32_16x16x32_bf16 v[126:129], v[140:143], v[204:207], v[126:129]
	v_mfma_f32_16x16x32_bf16 v[122:125], v[154:157], v[204:207], v[122:125]
	v_mfma_f32_16x16x32_bf16 v[110:113], v[140:143], v[212:215], v[110:113]
	v_mfma_f32_16x16x32_bf16 v[106:109], v[154:157], v[212:215], v[106:109]
	v_mfma_f32_16x16x32_bf16 v[94:97], v[140:143], v[220:223], v[94:97]
	v_mfma_f32_16x16x32_bf16 v[90:93], v[154:157], v[220:223], v[90:93]
	v_mfma_f32_16x16x32_bf16 v[78:81], v[140:143], v[228:231], v[78:81]
	v_mfma_f32_16x16x32_bf16 v[74:77], v[154:157], v[228:231], v[74:77]
	v_mfma_f32_16x16x32_bf16 v[126:129], v[150:153], v[208:211], v[126:129]
	v_mfma_f32_16x16x32_bf16 v[122:125], v[158:161], v[208:211], v[122:125]
	v_mfma_f32_16x16x32_bf16 v[110:113], v[150:153], v[216:219], v[110:113]
	v_mfma_f32_16x16x32_bf16 v[106:109], v[158:161], v[216:219], v[106:109]
	v_mfma_f32_16x16x32_bf16 v[94:97], v[150:153], v[224:227], v[94:97]
	v_mfma_f32_16x16x32_bf16 v[90:93], v[158:161], v[224:227], v[90:93]
	v_mfma_f32_16x16x32_bf16 v[78:81], v[150:153], v[244:247], v[78:81]
	v_mfma_f32_16x16x32_bf16 v[74:77], v[158:161], v[244:247], v[74:77]
	s_setprio 0
	s_setprio 1
	v_mfma_f32_16x16x32_bf16 v[118:121], v[162:165], v[204:207], v[118:121]
	v_mfma_f32_16x16x32_bf16 v[114:117], v[196:199], v[204:207], v[114:117]
	v_mfma_f32_16x16x32_bf16 v[102:105], v[162:165], v[212:215], v[102:105]
	v_mfma_f32_16x16x32_bf16 v[98:101], v[196:199], v[212:215], v[98:101]
	v_mfma_f32_16x16x32_bf16 v[86:89], v[162:165], v[220:223], v[86:89]
	v_mfma_f32_16x16x32_bf16 v[82:85], v[196:199], v[220:223], v[82:85]
	v_mfma_f32_16x16x32_bf16 v[70:73], v[162:165], v[228:231], v[70:73]
	v_mfma_f32_16x16x32_bf16 v[66:69], v[196:199], v[228:231], v[66:69]
	v_mfma_f32_16x16x32_bf16 v[118:121], v[192:195], v[208:211], v[118:121]
	v_mfma_f32_16x16x32_bf16 v[114:117], v[200:203], v[208:211], v[114:117]
	v_mfma_f32_16x16x32_bf16 v[102:105], v[192:195], v[216:219], v[102:105]
	v_mfma_f32_16x16x32_bf16 v[98:101], v[200:203], v[216:219], v[98:101]
	v_mfma_f32_16x16x32_bf16 v[86:89], v[192:195], v[224:227], v[86:89]
	s_setprio 3
	s_barrier
	v_mfma_f32_16x16x32_bf16 v[82:85], v[200:203], v[224:227], v[82:85]
	v_mfma_f32_16x16x32_bf16 v[70:73], v[192:195], v[244:247], v[70:73]
	v_mfma_f32_16x16x32_bf16 v[66:69], v[200:203], v[244:247], v[66:69]
	s_setprio 0
	s_add_i32 s48, s48, s33
	v_lshl_add_u64 v[144:145], s[22:23], 0, v[0:1]
	s_mov_b32 m0, s48
	ds_read_b128 v[204:207], v149 offset:16384
	ds_read_b128 v[208:211], v149 offset:17408
	ds_read_b128 v[212:215], v149 offset:18432
	ds_read_b128 v[216:219], v149 offset:19456
	ds_read_b128 v[220:223], v149 offset:20480
	ds_read_b128 v[224:227], v149 offset:21504
	ds_read_b128 v[228:231], v149 offset:22528
	ds_read_b128 v[244:247], v149 offset:23552
	global_load_lds_dwordx4 v[144:145], off
	s_add_i32 m0, s48, 0x2000
	s_add_u32 s48, s22, 0x40000
	v_lshl_add_u64 v[232:233], s[22:23], 0, v[130:131]
	s_addc_u32 s49, s23, 0
	s_add_i32 s50, s50, s33
	global_load_lds_dwordx4 v[232:233], off
	v_lshl_add_u64 v[236:237], s[48:49], 0, v[0:1]
	s_mov_b32 m0, s50
	v_lshl_add_u64 v[248:249], s[24:25], 0, v[132:133]
	global_load_lds_dwordx4 v[236:237], off
	v_lshl_add_u64 v[236:237], s[48:49], 0, v[130:131]
	s_add_i32 m0, s50, 0x2000
	s_nop 0
	global_load_lds_dwordx4 v[236:237], off
	v_lshl_add_u64 v[236:237], s[24:25], 0, v[134:135]
	s_mov_b32 m0, s35
	s_nop 0
	global_load_lds_dwordx4 v[236:237], off
	s_mov_b32 m0, s36
	s_nop 0
	global_load_lds_dwordx4 v[248:249], off
	s_waitcnt vmcnt(8)
	s_waitcnt lgkmcnt(0)
	s_barrier
; #define PG8_STAGE(bufoff, gbase, voff) do { _Pragma("unroll") for (int _i = 0; _i < 2; ++_i) \
;         __builtin_amdgcn_global_load_lds((const unsigned*)((const char*)(gbase) + (voff)[_i]), (PG8_LAS unsigned*)(lds + (bufoff) + ldsw + _i * 8192), 16, 0, 0); } while (0)
; #define PG8_LDA(dst, b, h) do { _Pragma("unroll") for (int m = 0; m < 4; ++m) _Pragma("unroll") for (int k = 0; k < 2; ++k) dst[m][k] = *(const PG8_LAS bf16x8*)(lds + PG8_SA(b, h) + aoff + m * 2048 + k * 1024); } while (0)
; #define PG8_LDB(dst, b, h) do { _Pragma("unroll") for (int n = 0; n < 2; ++n) _Pragma("unroll") for (int k = 0; k < 2; ++k) dst[n][k] = *(const PG8_LAS bf16x8*)(lds + PG8_SB(b, h) + boff + n * 2048 + k * 1024); } while (0)
; #define PG8_MMA(ai, bj, At, Bt) do { __builtin_amdgcn_s_setprio(1); _Pragma("unroll") for (int m = 0; m < 4; ++m) _Pragma("unroll") for (int n = 0; n < 2; ++n) _Pragma("unroll") for (int k = 0; k < 2; ++k) \
;         acc[ai][bj][m][n] = __builtin_amdgcn_mfma_f32_16x16x32_bf16(Bt[n][k], At[m][k], acc[ai][bj][m][n], 0, 0, 0); __builtin_amdgcn_s_setprio(0); } while (0)
; #define PG8_WAIT_V(n) asm volatile("s_waitcnt vmcnt(" #n ")" ::: "memory")
; #define PG8_WAIT_L(n) asm volatile("s_waitcnt lgkmcnt(" #n ")" ::: "memory")
; #define PG8_BAR __builtin_amdgcn_s_barrier()
; #define PG8_SCHED __builtin_amdgcn_sched_barrier(0)
; template <class Epi, class Sched, bool ALIGN_EPI = false, bool SP2 = false>
; __device__ __forceinline__ void gemm_phase(PG8_LAS unsigned char* lds, const Gemm g, const Sched& S, const Epi& E) {
;     ...
;             PG8_WAIT_V(8); PG8_WAIT_L(0); PG8_BAR; PG8_MMA(1, 0, At, B0); PG8_MMA(1, 1, At, B1); PG8_BAR; PG8_SCHED;
;             PG8_LDB(B0, 1, 0); PG8_LDB(B1, 1, 1); PG8_SCHED; PG8_LDA(At, 1, 0); PG8_STAGE(PG8_SA(0, 1), a2 + hstep, voffA);
;             PG8_WAIT_V(8); PG8_WAIT_L(0); PG8_BAR; PG8_MMA(0, 0, At, B0); PG8_MMA(0, 1, At, B1); PG8_BAR; PG8_SCHED;
	s_setprio 1
	s_waitcnt lgkmcnt(0)
	v_mfma_f32_16x16x32_bf16 v[62:65], v[140:143], v[204:207], v[62:65]
	v_mfma_f32_16x16x32_bf16 v[58:61], v[154:157], v[204:207], v[58:61]
	v_mfma_f32_16x16x32_bf16 v[46:49], v[140:143], v[212:215], v[46:49]
	v_mfma_f32_16x16x32_bf16 v[42:45], v[154:157], v[212:215], v[42:45]
	v_mfma_f32_16x16x32_bf16 v[30:33], v[140:143], v[220:223], v[30:33]
	v_mfma_f32_16x16x32_bf16 v[26:29], v[154:157], v[220:223], v[26:29]
	v_mfma_f32_16x16x32_bf16 v[14:17], v[140:143], v[228:231], v[14:17]
	v_mfma_f32_16x16x32_bf16 v[10:13], v[154:157], v[228:231], v[10:13]
	v_mfma_f32_16x16x32_bf16 v[62:65], v[150:153], v[208:211], v[62:65]
	v_mfma_f32_16x16x32_bf16 v[58:61], v[158:161], v[208:211], v[58:61]
	v_mfma_f32_16x16x32_bf16 v[46:49], v[150:153], v[216:219], v[46:49]
	v_mfma_f32_16x16x32_bf16 v[42:45], v[158:161], v[216:219], v[42:45]
	v_mfma_f32_16x16x32_bf16 v[30:33], v[150:153], v[224:227], v[30:33]
	v_mfma_f32_16x16x32_bf16 v[26:29], v[158:161], v[224:227], v[26:29]
	v_mfma_f32_16x16x32_bf16 v[14:17], v[150:153], v[244:247], v[14:17]
	v_mfma_f32_16x16x32_bf16 v[10:13], v[158:161], v[244:247], v[10:13]
	s_setprio 0
	s_setprio 1
	v_mfma_f32_16x16x32_bf16 v[54:57], v[162:165], v[204:207], v[54:57]
	v_mfma_f32_16x16x32_bf16 v[50:53], v[196:199], v[204:207], v[50:53]
	v_mfma_f32_16x16x32_bf16 v[38:41], v[162:165], v[212:215], v[38:41]
	v_mfma_f32_16x16x32_bf16 v[34:37], v[196:199], v[212:215], v[34:37]
	v_mfma_f32_16x16x32_bf16 v[22:25], v[162:165], v[220:223], v[22:25]
	v_mfma_f32_16x16x32_bf16 v[18:21], v[196:199], v[220:223], v[18:21]
	v_mfma_f32_16x16x32_bf16 v[6:9], v[162:165], v[228:231], v[6:9]
	v_mfma_f32_16x16x32_bf16 v[2:5], v[196:199], v[228:231], v[2:5]
	v_mfma_f32_16x16x32_bf16 v[54:57], v[192:195], v[208:211], v[54:57]
	v_mfma_f32_16x16x32_bf16 v[50:53], v[200:203], v[208:211], v[50:53]
	v_mfma_f32_16x16x32_bf16 v[38:41], v[192:195], v[216:219], v[38:41]
	v_mfma_f32_16x16x32_bf16 v[34:37], v[200:203], v[216:219], v[34:37]
	v_mfma_f32_16x16x32_bf16 v[22:25], v[192:195], v[224:227], v[22:25]
	s_setprio 3
	s_barrier
	v_mfma_f32_16x16x32_bf16 v[18:21], v[200:203], v[224:227], v[18:21]
	v_mfma_f32_16x16x32_bf16 v[6:9], v[192:195], v[244:247], v[6:9]
	v_mfma_f32_16x16x32_bf16 v[2:5], v[200:203], v[244:247], v[2:5]
	s_setprio 0
	s_add_i32 s48, 0, 0x18000
	s_add_i32 s49, 0, 0x1c000
	v_add_u32_e32 v158, s48, v147
	v_add_u32_e32 v182, s49, v147
	ds_read_b128 v[140:143], v158
	ds_read_b128 v[150:153], v158 offset:1024
	ds_read_b128 v[154:157], v158 offset:2048
	ds_read_b128 v[158:161], v158 offset:3072
	ds_read_b128 v[162:165], v182
	ds_read_b128 v[192:195], v182 offset:1024
	ds_read_b128 v[196:199], v182 offset:2048
	ds_read_b128 v[200:203], v182 offset:3072
	s_add_u32 s24, s24, 0x40000
	s_addc_u32 s25, s25, 0
	s_mov_b32 m0, s37
	v_lshl_add_u64 v[250:251], s[24:25], 0, v[134:135]
	ds_read_b128 v[204:207], v149 offset:32768
	ds_read_b128 v[208:211], v149 offset:33792
	ds_read_b128 v[212:215], v149 offset:34816
	ds_read_b128 v[216:219], v149 offset:35840
	ds_read_b128 v[220:223], v149 offset:36864
	ds_read_b128 v[224:227], v149 offset:37888
	ds_read_b128 v[228:231], v149 offset:38912
	ds_read_b128 v[244:247], v149 offset:39936
	global_load_lds_dwordx4 v[250:251], off
	v_lshl_add_u64 v[250:251], s[24:25], 0, v[132:133]
	s_mov_b32 m0, s38
	s_nop 0
	global_load_lds_dwordx4 v[250:251], off
	s_waitcnt vmcnt(8)
	s_waitcnt lgkmcnt(0)
	s_barrier
	s_setprio 1
	s_waitcnt lgkmcnt(0)
	v_mfma_f32_16x16x32_bf16 v[126:129], v[140:143], v[204:207], v[126:129]
	v_mfma_f32_16x16x32_bf16 v[122:125], v[154:157], v[204:207], v[122:125]
	v_mfma_f32_16x16x32_bf16 v[110:113], v[140:143], v[212:215], v[110:113]
	v_mfma_f32_16x16x32_bf16 v[106:109], v[154:157], v[212:215], v[106:109]
	v_mfma_f32_16x16x32_bf16 v[94:97], v[140:143], v[220:223], v[94:97]
	v_mfma_f32_16x16x32_bf16 v[90:93], v[154:157], v[220:223], v[90:93]
	v_mfma_f32_16x16x32_bf16 v[78:81], v[140:143], v[228:231], v[78:81]
	v_mfma_f32_16x16x32_bf16 v[74:77], v[154:157], v[228:231], v[74:77]
	v_mfma_f32_16x16x32_bf16 v[126:129], v[150:153], v[208:211], v[126:129]
	v_mfma_f32_16x16x32_bf16 v[122:125], v[158:161], v[208:211], v[122:125]
	v_mfma_f32_16x16x32_bf16 v[110:113], v[150:153], v[216:219], v[110:113]
	v_mfma_f32_16x16x32_bf16 v[106:109], v[158:161], v[216:219], v[106:109]
	v_mfma_f32_16x16x32_bf16 v[94:97], v[150:153], v[224:227], v[94:97]
	v_mfma_f32_16x16x32_bf16 v[90:93], v[158:161], v[224:227], v[90:93]
	v_mfma_f32_16x16x32_bf16 v[78:81], v[150:153], v[244:247], v[78:81]
	v_mfma_f32_16x16x32_bf16 v[74:77], v[158:161], v[244:247], v[74:77]
	s_setprio 0
	s_setprio 1
	v_mfma_f32_16x16x32_bf16 v[118:121], v[162:165], v[204:207], v[118:121]
	v_mfma_f32_16x16x32_bf16 v[114:117], v[196:199], v[204:207], v[114:117]
	v_mfma_f32_16x16x32_bf16 v[102:105], v[162:165], v[212:215], v[102:105]
	v_mfma_f32_16x16x32_bf16 v[98:101], v[196:199], v[212:215], v[98:101]
	v_mfma_f32_16x16x32_bf16 v[86:89], v[162:165], v[220:223], v[86:89]
	v_mfma_f32_16x16x32_bf16 v[82:85], v[196:199], v[220:223], v[82:85]
	v_mfma_f32_16x16x32_bf16 v[70:73], v[162:165], v[228:231], v[70:73]
	v_mfma_f32_16x16x32_bf16 v[66:69], v[196:199], v[228:231], v[66:69]
	v_mfma_f32_16x16x32_bf16 v[118:121], v[192:195], v[208:211], v[118:121]
	v_mfma_f32_16x16x32_bf16 v[114:117], v[200:203], v[208:211], v[114:117]
	v_mfma_f32_16x16x32_bf16 v[102:105], v[192:195], v[216:219], v[102:105]
	v_mfma_f32_16x16x32_bf16 v[98:101], v[200:203], v[216:219], v[98:101]
	v_mfma_f32_16x16x32_bf16 v[86:89], v[192:195], v[224:227], v[86:89]
	s_setprio 3
	s_barrier
; #define PG8_STAGE(bufoff, gbase, voff) do { _Pragma("unroll") for (int _i = 0; _i < 2; ++_i) \
;         __builtin_amdgcn_global_load_lds((const unsigned*)((const char*)(gbase) + (voff)[_i]), (PG8_LAS unsigned*)(lds + (bufoff) + ldsw + _i * 8192), 16, 0, 0); } while (0)
; #define PG8_LDA(dst, b, h) do { _Pragma("unroll") for (int m = 0; m < 4; ++m) _Pragma("unroll") for (int k = 0; k < 2; ++k) dst[m][k] = *(const PG8_LAS bf16x8*)(lds + PG8_SA(b, h) + aoff + m * 2048 + k * 1024); } while (0)
; #define PG8_MMA(ai, bj, At, Bt) do { __builtin_amdgcn_s_setprio(1); _Pragma("unroll") for (int m = 0; m < 4; ++m) _Pragma("unroll") for (int n = 0; n < 2; ++n) _Pragma("unroll") for (int k = 0; k < 2; ++k) \
;         acc[ai][bj][m][n] = __builtin_amdgcn_mfma_f32_16x16x32_bf16(Bt[n][k], At[m][k], acc[ai][bj][m][n], 0, 0, 0); __builtin_amdgcn_s_setprio(0); } while (0)
; #define PG8_WAIT_V(n) asm volatile("s_waitcnt vmcnt(" #n ")" ::: "memory")
; #define PG8_WAIT_L(n) asm volatile("s_waitcnt lgkmcnt(" #n ")" ::: "memory")
; #define PG8_BAR __builtin_amdgcn_s_barrier()
; #define PG8_SCHED __builtin_amdgcn_sched_barrier(0)
; template <class Epi, class Sched, bool ALIGN_EPI = false, bool SP2 = false>
; __device__ __forceinline__ void gemm_phase(PG8_LAS unsigned char* lds, const Gemm g, const Sched& S, const Epi& E) {
;     ...
;         for (int t = 0; t < nt; t += 2) {
;     ...
;             PG8_WAIT_V(8); PG8_WAIT_L(0); PG8_BAR; PG8_MMA(0, 0, At, B0); PG8_MMA(0, 1, At, B1); PG8_BAR; PG8_SCHED;
;             PG8_LDA(At, 1, 1); PG8_STAGE(PG8_SB(1, 0), b3, voffB); PG8_STAGE(PG8_SB(1, 1), b3 + hstep, voffB); PG8_STAGE(PG8_SA(1, 0), a3, voffA);
;             PG8_WAIT_V(8); PG8_WAIT_L(0); PG8_BAR; PG8_MMA(1, 0, At, B0); PG8_MMA(1, 1, At, B1); PG8_BAR; PG8_SCHED;
	v_mfma_f32_16x16x32_bf16 v[82:85], v[200:203], v[224:227], v[82:85]
	v_mfma_f32_16x16x32_bf16 v[70:73], v[192:195], v[244:247], v[70:73]
	v_mfma_f32_16x16x32_bf16 v[66:69], v[200:203], v[244:247], v[66:69]
	s_setprio 0
	s_add_i32 s24, s48, s33
	v_lshl_add_u64 v[144:145], v[144:145], 0, s[52:53]
	s_mov_b32 m0, s24
	ds_read_b128 v[204:207], v149 offset:49152
	ds_read_b128 v[208:211], v149 offset:50176
	ds_read_b128 v[212:215], v149 offset:51200
	ds_read_b128 v[216:219], v149 offset:52224
	ds_read_b128 v[220:223], v149 offset:53248
	ds_read_b128 v[224:227], v149 offset:54272
	ds_read_b128 v[228:231], v149 offset:55296
	ds_read_b128 v[244:247], v149 offset:56320
	global_load_lds_dwordx4 v[144:145], off
	s_add_i32 m0, s24, 0x2000
	s_add_u32 s22, s22, 0x40080
	v_lshl_add_u64 v[144:145], v[232:233], 0, s[52:53]
	s_addc_u32 s23, s23, 0
	s_add_i32 s24, s49, s33
	global_load_lds_dwordx4 v[144:145], off
	v_lshl_add_u64 v[144:145], s[22:23], 0, v[0:1]
	s_mov_b32 m0, s24
	s_nop 0
	global_load_lds_dwordx4 v[144:145], off
	v_lshl_add_u64 v[144:145], s[22:23], 0, v[130:131]
	s_add_i32 m0, s24, 0x2000
	s_nop 0
	global_load_lds_dwordx4 v[144:145], off
	v_lshl_add_u64 v[144:145], v[236:237], 0, s[52:53]
	s_mov_b32 m0, s39
	s_nop 0
	global_load_lds_dwordx4 v[144:145], off
	v_lshl_add_u64 v[144:145], v[248:249], 0, s[52:53]
	s_mov_b32 m0, s40
	s_nop 0
	global_load_lds_dwordx4 v[144:145], off
	s_waitcnt vmcnt(8)
	s_waitcnt lgkmcnt(0)
	s_barrier
	s_setprio 1
	s_waitcnt lgkmcnt(0)
	v_mfma_f32_16x16x32_bf16 v[62:65], v[140:143], v[204:207], v[62:65]
	v_mfma_f32_16x16x32_bf16 v[58:61], v[154:157], v[204:207], v[58:61]
	v_mfma_f32_16x16x32_bf16 v[46:49], v[140:143], v[212:215], v[46:49]
	v_mfma_f32_16x16x32_bf16 v[42:45], v[154:157], v[212:215], v[42:45]
	v_mfma_f32_16x16x32_bf16 v[30:33], v[140:143], v[220:223], v[30:33]
	v_mfma_f32_16x16x32_bf16 v[26:29], v[154:157], v[220:223], v[26:29]
	v_mfma_f32_16x16x32_bf16 v[14:17], v[140:143], v[228:231], v[14:17]
	v_mfma_f32_16x16x32_bf16 v[10:13], v[154:157], v[228:231], v[10:13]
	v_mfma_f32_16x16x32_bf16 v[62:65], v[150:153], v[208:211], v[62:65]
	v_mfma_f32_16x16x32_bf16 v[58:61], v[158:161], v[208:211], v[58:61]
	v_mfma_f32_16x16x32_bf16 v[46:49], v[150:153], v[216:219], v[46:49]
	v_mfma_f32_16x16x32_bf16 v[42:45], v[158:161], v[216:219], v[42:45]
	v_mfma_f32_16x16x32_bf16 v[30:33], v[150:153], v[224:227], v[30:33]
	v_mfma_f32_16x16x32_bf16 v[26:29], v[158:161], v[224:227], v[26:29]
	v_mfma_f32_16x16x32_bf16 v[14:17], v[150:153], v[244:247], v[14:17]
	v_mfma_f32_16x16x32_bf16 v[10:13], v[158:161], v[244:247], v[10:13]
	s_setprio 0
	s_setprio 1
	v_mfma_f32_16x16x32_bf16 v[54:57], v[162:165], v[204:207], v[54:57]
	v_mfma_f32_16x16x32_bf16 v[50:53], v[196:199], v[204:207], v[50:53]
	v_mfma_f32_16x16x32_bf16 v[38:41], v[162:165], v[212:215], v[38:41]
	v_mfma_f32_16x16x32_bf16 v[34:37], v[196:199], v[212:215], v[34:37]
	v_mfma_f32_16x16x32_bf16 v[22:25], v[162:165], v[220:223], v[22:25]
	v_mfma_f32_16x16x32_bf16 v[18:21], v[196:199], v[220:223], v[18:21]
	v_mfma_f32_16x16x32_bf16 v[6:9], v[162:165], v[228:231], v[6:9]
	v_mfma_f32_16x16x32_bf16 v[2:5], v[196:199], v[228:231], v[2:5]
	v_mfma_f32_16x16x32_bf16 v[54:57], v[192:195], v[208:211], v[54:57]
	v_mfma_f32_16x16x32_bf16 v[50:53], v[200:203], v[208:211], v[50:53]
	v_mfma_f32_16x16x32_bf16 v[38:41], v[192:195], v[216:219], v[38:41]
	v_mfma_f32_16x16x32_bf16 v[34:37], v[200:203], v[216:219], v[34:37]
	v_mfma_f32_16x16x32_bf16 v[22:25], v[192:195], v[224:227], v[22:25]
	s_setprio 3
	s_barrier
	v_mfma_f32_16x16x32_bf16 v[18:21], v[200:203], v[224:227], v[18:21]
	v_mfma_f32_16x16x32_bf16 v[6:9], v[192:195], v[244:247], v[6:9]
	v_mfma_f32_16x16x32_bf16 v[2:5], v[200:203], v[244:247], v[2:5]
	s_setprio 0
	s_add_i32 s47, s47, 2
	s_add_u32 s45, s45, 0x100
	s_addc_u32 s46, s46, 0
	s_add_u32 s20, s20, 0x100
	s_addc_u32 s21, s21, 0
	s_cmp_gt_u32 s47, 13
	s_cbranch_scc0 .LBB0_752
	s_and_b64 vcc, exec, s[8:9]
	s_cbranch_vccz .LBB0_755
	s_barrier

; #define PG8_STAGE(bufoff, gbase, voff) do { _Pragma("unroll") for (int _i = 0; _i < 2; ++_i) \
;         __builtin_amdgcn_global_load_lds((const unsigned*)((const char*)(gbase) + (voff)[_i]), (PG8_LAS unsigned*)(lds + (bufoff) + ldsw + _i * 8192), 16, 0, 0); } while (0)
; #define PG8_LDA(dst, b, h) do { _Pragma("unroll") for (int m = 0; m < 4; ++m) _Pragma("unroll") for (int k = 0; k < 2; ++k) dst[m][k] = *(const PG8_LAS bf16x8*)(lds + PG8_SA(b, h) + aoff + m * 2048 + k * 1024); } while (0)
; #define PG8_LDB(dst, b, h) do { _Pragma("unroll") for (int n = 0; n < 2; ++n) _Pragma("unroll") for (int k = 0; k < 2; ++k) dst[n][k] = *(const PG8_LAS bf16x8*)(lds + PG8_SB(b, h) + boff + n * 2048 + k * 1024); } while (0)
; #define PG8_MMA(ai, bj, At, Bt) do { __builtin_amdgcn_s_setprio(1); _Pragma("unroll") for (int m = 0; m < 4; ++m) _Pragma("unroll") for (int n = 0; n < 2; ++n) _Pragma("unroll") for (int k = 0; k < 2; ++k) \
;         acc[ai][bj][m][n] = __builtin_amdgcn_mfma_f32_16x16x32_bf16(Bt[n][k], At[m][k], acc[ai][bj][m][n], 0, 0, 0); __builtin_amdgcn_s_setprio(0); } while (0)
; #define PG8_WAIT_V(n) asm volatile("s_waitcnt vmcnt(" #n ")" ::: "memory")
; #define PG8_WAIT_L(n) asm volatile("s_waitcnt lgkmcnt(" #n ")" ::: "memory")
; template <class Epi, class Sched, bool ALIGN_EPI = false, bool SP2 = false>
; __device__ __forceinline__ void gemm_phase(PG8_LAS unsigned char* lds, const Gemm g, const Sched& S, const Epi& E) {
;     ...
;             const bool last = (t == nt - 2);
;             const char* a1 = cA + (size_t)(t + 1) * kstep;
;             const char* a2 = last ? nA : cA + (size_t)(t + 2) * kstep; const char* b2 = last ? nB : cB + (size_t)(t + 2) * kstep;
;             const char* a3 = a2 + kstep; const char* b3 = b2 + kstep;
;             if (last && has_next) S.a_ready(nxt);
;             if constexpr (SP2) {
;             PG8_LDB(B0, 0, 0); PG8_LDB(B1, 0, 1); PG8_SCHED; PG8_LDA(At, 0, 0); PG8_STAGE(PG8_SA(1, 1), a1 + hstep, voffA);
;             PG8_WAIT_V(8); PG8_WAIT_L(0); PG8_BAR; PG8_MMA(0, 0, At, B0); PG8_MMA(0, 1, At, B1); PG8_BAR; PG8_SCHED;
;             PG8_LDA(At, 0, 1); PG8_STAGE(PG8_SB(0, 0), b2, voffB); PG8_STAGE(PG8_SB(0, 1), b2 + hstep, voffB); PG8_STAGE(PG8_SA(0, 0), a2, voffA);
;             PG8_WAIT_V(8); PG8_WAIT_L(0); PG8_BAR; PG8_MMA(1, 0, At, B0); PG8_MMA(1, 1, At, B1); PG8_BAR; PG8_SCHED;
.LBB0_839:
	s_add_u32 s22, s10, 0x100
	s_addc_u32 s23, s11, 0
	s_add_i32 s53, 0, 0x10000
	s_cmp_eq_u32 s52, 40
	s_cselect_b32 s27, s1, s23
	s_cselect_b32 s26, s0, s22
	s_cselect_b32 s25, s21, s51
	s_cselect_b32 s24, s20, s50
	s_add_i32 s54, 0, 0x14000
	v_add_u32_e32 v156, s53, v149
	v_add_u32_e32 v164, s54, v149
	ds_read_b128 v[140:143], v156
	ds_read_b128 v[144:147], v156 offset:1024
	ds_read_b128 v[152:155], v156 offset:2048
	ds_read_b128 v[156:159], v156 offset:3072
	ds_read_b128 v[160:163], v164
	ds_read_b128 v[192:195], v164 offset:1024
	ds_read_b128 v[196:199], v164 offset:2048
	ds_read_b128 v[200:203], v164 offset:3072
	v_lshl_add_u64 v[164:165], s[10:11], 0, v[138:139]
	s_add_i32 m0, s36, 0xc000
	ds_read_b128 v[204:207], v151
	ds_read_b128 v[208:211], v151 offset:1024
	ds_read_b128 v[212:215], v151 offset:2048
	ds_read_b128 v[216:219], v151 offset:3072
	ds_read_b128 v[220:223], v151 offset:4096
	ds_read_b128 v[224:227], v151 offset:5120
	ds_read_b128 v[228:231], v151 offset:6144
	ds_read_b128 v[244:247], v151 offset:7168
	global_load_lds_dwordx4 v[164:165], off
	v_lshl_add_u64 v[164:165], s[10:11], 0, v[136:137]
	s_add_i32 m0, s36, 0xe000
	s_nop 0
	global_load_lds_dwordx4 v[164:165], off
	s_waitcnt vmcnt(8)
	s_waitcnt lgkmcnt(0)
	s_barrier
	s_setprio 1
	s_waitcnt lgkmcnt(0)
	v_mfma_f32_16x16x32_bf16 v[126:129], v[140:143], v[204:207], v[126:129]
	v_mfma_f32_16x16x32_bf16 v[122:125], v[152:155], v[204:207], v[122:125]
	v_mfma_f32_16x16x32_bf16 v[110:113], v[140:143], v[212:215], v[110:113]
	v_mfma_f32_16x16x32_bf16 v[106:109], v[152:155], v[212:215], v[106:109]
	v_mfma_f32_16x16x32_bf16 v[94:97], v[140:143], v[220:223], v[94:97]
	v_mfma_f32_16x16x32_bf16 v[90:93], v[152:155], v[220:223], v[90:93]
	v_mfma_f32_16x16x32_bf16 v[78:81], v[140:143], v[228:231], v[78:81]
	v_mfma_f32_16x16x32_bf16 v[74:77], v[152:155], v[228:231], v[74:77]
	v_mfma_f32_16x16x32_bf16 v[126:129], v[144:147], v[208:211], v[126:129]
	v_mfma_f32_16x16x32_bf16 v[122:125], v[156:159], v[208:211], v[122:125]
	v_mfma_f32_16x16x32_bf16 v[110:113], v[144:147], v[216:219], v[110:113]
	v_mfma_f32_16x16x32_bf16 v[106:109], v[156:159], v[216:219], v[106:109]
	v_mfma_f32_16x16x32_bf16 v[94:97], v[144:147], v[224:227], v[94:97]
	v_mfma_f32_16x16x32_bf16 v[90:93], v[156:159], v[224:227], v[90:93]
	v_mfma_f32_16x16x32_bf16 v[78:81], v[144:147], v[244:247], v[78:81]
	v_mfma_f32_16x16x32_bf16 v[74:77], v[156:159], v[244:247], v[74:77]
	s_setprio 0
	s_setprio 1
	v_mfma_f32_16x16x32_bf16 v[118:121], v[160:163], v[204:207], v[118:121]
	v_mfma_f32_16x16x32_bf16 v[114:117], v[196:199], v[204:207], v[114:117]
	v_mfma_f32_16x16x32_bf16 v[102:105], v[160:163], v[212:215], v[102:105]
	v_mfma_f32_16x16x32_bf16 v[98:101], v[196:199], v[212:215], v[98:101]
	v_mfma_f32_16x16x32_bf16 v[86:89], v[160:163], v[220:223], v[86:89]
	v_mfma_f32_16x16x32_bf16 v[82:85], v[196:199], v[220:223], v[82:85]
	v_mfma_f32_16x16x32_bf16 v[70:73], v[160:163], v[228:231], v[70:73]
	v_mfma_f32_16x16x32_bf16 v[66:69], v[196:199], v[228:231], v[66:69]
	v_mfma_f32_16x16x32_bf16 v[118:121], v[192:195], v[208:211], v[118:121]
	v_mfma_f32_16x16x32_bf16 v[114:117], v[200:203], v[208:211], v[114:117]
	v_mfma_f32_16x16x32_bf16 v[102:105], v[192:195], v[216:219], v[102:105]
	v_mfma_f32_16x16x32_bf16 v[98:101], v[200:203], v[216:219], v[98:101]
	v_mfma_f32_16x16x32_bf16 v[86:89], v[192:195], v[224:227], v[86:89]
	s_setprio 3
	s_barrier
	v_mfma_f32_16x16x32_bf16 v[82:85], v[200:203], v[224:227], v[82:85]
	v_mfma_f32_16x16x32_bf16 v[70:73], v[192:195], v[244:247], v[70:73]
	v_mfma_f32_16x16x32_bf16 v[66:69], v[200:203], v[244:247], v[66:69]
	s_setprio 0
	s_add_i32 s10, s53, s30
	v_lshl_add_u64 v[164:165], s[24:25], 0, v[0:1]
	s_mov_b32 m0, s10
	ds_read_b128 v[204:207], v151 offset:16384
	ds_read_b128 v[208:211], v151 offset:17408
	ds_read_b128 v[212:215], v151 offset:18432
	ds_read_b128 v[216:219], v151 offset:19456
	ds_read_b128 v[220:223], v151 offset:20480
	ds_read_b128 v[224:227], v151 offset:21504
	ds_read_b128 v[228:231], v151 offset:22528
	ds_read_b128 v[244:247], v151 offset:23552
	global_load_lds_dwordx4 v[164:165], off
	s_add_i32 m0, s10, 0x2000
	s_add_u32 s10, s24, 0xb0000
	v_lshl_add_u64 v[232:233], s[24:25], 0, v[134:135]
	s_addc_u32 s11, s25, 0
	s_add_i32 s53, s54, s30
	global_load_lds_dwordx4 v[232:233], off
	v_lshl_add_u64 v[236:237], s[10:11], 0, v[0:1]
	s_mov_b32 m0, s53
	v_lshl_add_u64 v[248:249], s[26:27], 0, v[132:133]
	global_load_lds_dwordx4 v[236:237], off
	v_lshl_add_u64 v[236:237], s[10:11], 0, v[134:135]
	s_add_i32 m0, s53, 0x2000
	s_nop 0
	global_load_lds_dwordx4 v[236:237], off
	v_lshl_add_u64 v[236:237], s[26:27], 0, v[130:131]
	s_mov_b32 m0, s36
	s_nop 0
	global_load_lds_dwordx4 v[236:237], off
	s_mov_b32 m0, s37
	s_nop 0
	global_load_lds_dwordx4 v[248:249], off
	s_waitcnt vmcnt(8)
	s_waitcnt lgkmcnt(0)
	s_barrier
; #define PG8_STAGE(bufoff, gbase, voff) do { _Pragma("unroll") for (int _i = 0; _i < 2; ++_i) \
;         __builtin_amdgcn_global_load_lds((const unsigned*)((const char*)(gbase) + (voff)[_i]), (PG8_LAS unsigned*)(lds + (bufoff) + ldsw + _i * 8192), 16, 0, 0); } while (0)
; #define PG8_LDA(dst, b, h) do { _Pragma("unroll") for (int m = 0; m < 4; ++m) _Pragma("unroll") for (int k = 0; k < 2; ++k) dst[m][k] = *(const PG8_LAS bf16x8*)(lds + PG8_SA(b, h) + aoff + m * 2048 + k * 1024); } while (0)
; #define PG8_LDB(dst, b, h) do { _Pragma("unroll") for (int n = 0; n < 2; ++n) _Pragma("unroll") for (int k = 0; k < 2; ++k) dst[n][k] = *(const PG8_LAS bf16x8*)(lds + PG8_SB(b, h) + boff + n * 2048 + k * 1024); } while (0)
; #define PG8_MMA(ai, bj, At, Bt) do { __builtin_amdgcn_s_setprio(1); _Pragma("unroll") for (int m = 0; m < 4; ++m) _Pragma("unroll") for (int n = 0; n < 2; ++n) _Pragma("unroll") for (int k = 0; k < 2; ++k) \
;         acc[ai][bj][m][n] = __builtin_amdgcn_mfma_f32_16x16x32_bf16(Bt[n][k], At[m][k], acc[ai][bj][m][n], 0, 0, 0); __builtin_amdgcn_s_setprio(0); } while (0)
; #define PG8_WAIT_V(n) asm volatile("s_waitcnt vmcnt(" #n ")" ::: "memory")
; #define PG8_WAIT_L(n) asm volatile("s_waitcnt lgkmcnt(" #n ")" ::: "memory")
; #define PG8_BAR __builtin_amdgcn_s_barrier()
; #define PG8_SCHED __builtin_amdgcn_sched_barrier(0)
; template <class Epi, class Sched, bool ALIGN_EPI = false, bool SP2 = false>
; __device__ __forceinline__ void gemm_phase(PG8_LAS unsigned char* lds, const Gemm g, const Sched& S, const Epi& E) {
;     ...
;             PG8_WAIT_V(8); PG8_WAIT_L(0); PG8_BAR; PG8_MMA(1, 0, At, B0); PG8_MMA(1, 1, At, B1); PG8_BAR; PG8_SCHED;
;             PG8_LDB(B0, 1, 0); PG8_LDB(B1, 1, 1); PG8_SCHED; PG8_LDA(At, 1, 0); PG8_STAGE(PG8_SA(0, 1), a2 + hstep, voffA);
;             PG8_WAIT_V(8); PG8_WAIT_L(0); PG8_BAR; PG8_MMA(0, 0, At, B0); PG8_MMA(0, 1, At, B1); PG8_BAR; PG8_SCHED;
	s_setprio 1
	s_waitcnt lgkmcnt(0)
	v_mfma_f32_16x16x32_bf16 v[62:65], v[140:143], v[204:207], v[62:65]
	v_mfma_f32_16x16x32_bf16 v[58:61], v[152:155], v[204:207], v[58:61]
	v_mfma_f32_16x16x32_bf16 v[46:49], v[140:143], v[212:215], v[46:49]
	v_mfma_f32_16x16x32_bf16 v[42:45], v[152:155], v[212:215], v[42:45]
	v_mfma_f32_16x16x32_bf16 v[30:33], v[140:143], v[220:223], v[30:33]
	v_mfma_f32_16x16x32_bf16 v[26:29], v[152:155], v[220:223], v[26:29]
	v_mfma_f32_16x16x32_bf16 v[14:17], v[140:143], v[228:231], v[14:17]
	v_mfma_f32_16x16x32_bf16 v[10:13], v[152:155], v[228:231], v[10:13]
	v_mfma_f32_16x16x32_bf16 v[62:65], v[144:147], v[208:211], v[62:65]
	v_mfma_f32_16x16x32_bf16 v[58:61], v[156:159], v[208:211], v[58:61]
	v_mfma_f32_16x16x32_bf16 v[46:49], v[144:147], v[216:219], v[46:49]
	v_mfma_f32_16x16x32_bf16 v[42:45], v[156:159], v[216:219], v[42:45]
	v_mfma_f32_16x16x32_bf16 v[30:33], v[144:147], v[224:227], v[30:33]
	v_mfma_f32_16x16x32_bf16 v[26:29], v[156:159], v[224:227], v[26:29]
	v_mfma_f32_16x16x32_bf16 v[14:17], v[144:147], v[244:247], v[14:17]
	v_mfma_f32_16x16x32_bf16 v[10:13], v[156:159], v[244:247], v[10:13]
	s_setprio 0
	s_setprio 1
	v_mfma_f32_16x16x32_bf16 v[54:57], v[160:163], v[204:207], v[54:57]
	v_mfma_f32_16x16x32_bf16 v[50:53], v[196:199], v[204:207], v[50:53]
	v_mfma_f32_16x16x32_bf16 v[38:41], v[160:163], v[212:215], v[38:41]
	v_mfma_f32_16x16x32_bf16 v[34:37], v[196:199], v[212:215], v[34:37]
	v_mfma_f32_16x16x32_bf16 v[22:25], v[160:163], v[220:223], v[22:25]
	v_mfma_f32_16x16x32_bf16 v[18:21], v[196:199], v[220:223], v[18:21]
	v_mfma_f32_16x16x32_bf16 v[6:9], v[160:163], v[228:231], v[6:9]
	v_mfma_f32_16x16x32_bf16 v[2:5], v[196:199], v[228:231], v[2:5]
	v_mfma_f32_16x16x32_bf16 v[54:57], v[192:195], v[208:211], v[54:57]
	v_mfma_f32_16x16x32_bf16 v[50:53], v[200:203], v[208:211], v[50:53]
	v_mfma_f32_16x16x32_bf16 v[38:41], v[192:195], v[216:219], v[38:41]
	v_mfma_f32_16x16x32_bf16 v[34:37], v[200:203], v[216:219], v[34:37]
	v_mfma_f32_16x16x32_bf16 v[22:25], v[192:195], v[224:227], v[22:25]
	s_setprio 3
	s_barrier
	v_mfma_f32_16x16x32_bf16 v[18:21], v[200:203], v[224:227], v[18:21]
	v_mfma_f32_16x16x32_bf16 v[6:9], v[192:195], v[244:247], v[6:9]
	v_mfma_f32_16x16x32_bf16 v[2:5], v[200:203], v[244:247], v[2:5]
	s_setprio 0
	s_add_i32 s53, 0, 0x18000
	s_add_i32 s54, 0, 0x1c000
	v_add_u32_e32 v156, s53, v149
	v_add_u32_e32 v182, s54, v149
	ds_read_b128 v[140:143], v156
	ds_read_b128 v[144:147], v156 offset:1024
	ds_read_b128 v[152:155], v156 offset:2048
	ds_read_b128 v[156:159], v156 offset:3072
	ds_read_b128 v[160:163], v182
	ds_read_b128 v[192:195], v182 offset:1024
	ds_read_b128 v[196:199], v182 offset:2048
	ds_read_b128 v[200:203], v182 offset:3072
	s_add_u32 s10, s26, 0xb0000
	s_addc_u32 s11, s27, 0
	s_mov_b32 m0, s38
	v_lshl_add_u64 v[250:251], s[10:11], 0, v[130:131]
	ds_read_b128 v[204:207], v151 offset:32768
	ds_read_b128 v[208:211], v151 offset:33792
	ds_read_b128 v[212:215], v151 offset:34816
	ds_read_b128 v[216:219], v151 offset:35840
	ds_read_b128 v[220:223], v151 offset:36864
	ds_read_b128 v[224:227], v151 offset:37888
	ds_read_b128 v[228:231], v151 offset:38912
	ds_read_b128 v[244:247], v151 offset:39936
	global_load_lds_dwordx4 v[250:251], off
	v_lshl_add_u64 v[250:251], s[10:11], 0, v[132:133]
	s_mov_b32 m0, s39
	s_nop 0
	global_load_lds_dwordx4 v[250:251], off
	s_waitcnt vmcnt(8)
	s_waitcnt lgkmcnt(0)
	s_barrier
	s_setprio 1
	s_waitcnt lgkmcnt(0)
	v_mfma_f32_16x16x32_bf16 v[126:129], v[140:143], v[204:207], v[126:129]
	v_mfma_f32_16x16x32_bf16 v[122:125], v[152:155], v[204:207], v[122:125]
	v_mfma_f32_16x16x32_bf16 v[110:113], v[140:143], v[212:215], v[110:113]
	v_mfma_f32_16x16x32_bf16 v[106:109], v[152:155], v[212:215], v[106:109]
	v_mfma_f32_16x16x32_bf16 v[94:97], v[140:143], v[220:223], v[94:97]
	v_mfma_f32_16x16x32_bf16 v[90:93], v[152:155], v[220:223], v[90:93]
	v_mfma_f32_16x16x32_bf16 v[78:81], v[140:143], v[228:231], v[78:81]
	v_mfma_f32_16x16x32_bf16 v[74:77], v[152:155], v[228:231], v[74:77]
	v_mfma_f32_16x16x32_bf16 v[126:129], v[144:147], v[208:211], v[126:129]
	v_mfma_f32_16x16x32_bf16 v[122:125], v[156:159], v[208:211], v[122:125]
	v_mfma_f32_16x16x32_bf16 v[110:113], v[144:147], v[216:219], v[110:113]
	v_mfma_f32_16x16x32_bf16 v[106:109], v[156:159], v[216:219], v[106:109]
	v_mfma_f32_16x16x32_bf16 v[94:97], v[144:147], v[224:227], v[94:97]
	v_mfma_f32_16x16x32_bf16 v[90:93], v[156:159], v[224:227], v[90:93]
	v_mfma_f32_16x16x32_bf16 v[78:81], v[144:147], v[244:247], v[78:81]
	v_mfma_f32_16x16x32_bf16 v[74:77], v[156:159], v[244:247], v[74:77]
	s_setprio 0
	s_setprio 1
	v_mfma_f32_16x16x32_bf16 v[118:121], v[160:163], v[204:207], v[118:121]
	v_mfma_f32_16x16x32_bf16 v[114:117], v[196:199], v[204:207], v[114:117]
	v_mfma_f32_16x16x32_bf16 v[102:105], v[160:163], v[212:215], v[102:105]
	v_mfma_f32_16x16x32_bf16 v[98:101], v[196:199], v[212:215], v[98:101]
	v_mfma_f32_16x16x32_bf16 v[86:89], v[160:163], v[220:223], v[86:89]
	v_mfma_f32_16x16x32_bf16 v[82:85], v[196:199], v[220:223], v[82:85]
	v_mfma_f32_16x16x32_bf16 v[70:73], v[160:163], v[228:231], v[70:73]
	v_mfma_f32_16x16x32_bf16 v[66:69], v[196:199], v[228:231], v[66:69]
	v_mfma_f32_16x16x32_bf16 v[118:121], v[192:195], v[208:211], v[118:121]
	v_mfma_f32_16x16x32_bf16 v[114:117], v[200:203], v[208:211], v[114:117]
	v_mfma_f32_16x16x32_bf16 v[102:105], v[192:195], v[216:219], v[102:105]
	v_mfma_f32_16x16x32_bf16 v[98:101], v[200:203], v[216:219], v[98:101]
	v_mfma_f32_16x16x32_bf16 v[86:89], v[192:195], v[224:227], v[86:89]
	s_setprio 3
	s_barrier
; #define PG8_STAGE(bufoff, gbase, voff) do { _Pragma("unroll") for (int _i = 0; _i < 2; ++_i) \
;         __builtin_amdgcn_global_load_lds((const unsigned*)((const char*)(gbase) + (voff)[_i]), (PG8_LAS unsigned*)(lds + (bufoff) + ldsw + _i * 8192), 16, 0, 0); } while (0)
; #define PG8_LDA(dst, b, h) do { _Pragma("unroll") for (int m = 0; m < 4; ++m) _Pragma("unroll") for (int k = 0; k < 2; ++k) dst[m][k] = *(const PG8_LAS bf16x8*)(lds + PG8_SA(b, h) + aoff + m * 2048 + k * 1024); } while (0)
; #define PG8_MMA(ai, bj, At, Bt) do { __builtin_amdgcn_s_setprio(1); _Pragma("unroll") for (int m = 0; m < 4; ++m) _Pragma("unroll") for (int n = 0; n < 2; ++n) _Pragma("unroll") for (int k = 0; k < 2; ++k) \
;         acc[ai][bj][m][n] = __builtin_amdgcn_mfma_f32_16x16x32_bf16(Bt[n][k], At[m][k], acc[ai][bj][m][n], 0, 0, 0); __builtin_amdgcn_s_setprio(0); } while (0)
; #define PG8_WAIT_V(n) asm volatile("s_waitcnt vmcnt(" #n ")" ::: "memory")
; #define PG8_WAIT_L(n) asm volatile("s_waitcnt lgkmcnt(" #n ")" ::: "memory")
; #define PG8_BAR __builtin_amdgcn_s_barrier()
; #define PG8_SCHED __builtin_amdgcn_sched_barrier(0)
; template <class Epi, class Sched, bool ALIGN_EPI = false, bool SP2 = false>
; __device__ __forceinline__ void gemm_phase(PG8_LAS unsigned char* lds, const Gemm g, const Sched& S, const Epi& E) {
;     ...
;         for (int t = 0; t < nt; t += 2) {
;     ...
;             PG8_WAIT_V(8); PG8_WAIT_L(0); PG8_BAR; PG8_MMA(0, 0, At, B0); PG8_MMA(0, 1, At, B1); PG8_BAR; PG8_SCHED;
;             PG8_LDA(At, 1, 1); PG8_STAGE(PG8_SB(1, 0), b3, voffB); PG8_STAGE(PG8_SB(1, 1), b3 + hstep, voffB); PG8_STAGE(PG8_SA(1, 0), a3, voffA);
;             PG8_WAIT_V(8); PG8_WAIT_L(0); PG8_BAR; PG8_MMA(1, 0, At, B0); PG8_MMA(1, 1, At, B1); PG8_BAR; PG8_SCHED;
	v_mfma_f32_16x16x32_bf16 v[82:85], v[200:203], v[224:227], v[82:85]
	v_mfma_f32_16x16x32_bf16 v[70:73], v[192:195], v[244:247], v[70:73]
	v_mfma_f32_16x16x32_bf16 v[66:69], v[200:203], v[244:247], v[66:69]
	s_setprio 0
	s_add_i32 s10, s53, s30
	v_lshl_add_u64 v[164:165], v[164:165], 0, s[56:57]
	s_mov_b32 m0, s10
	ds_read_b128 v[204:207], v151 offset:49152
	ds_read_b128 v[208:211], v151 offset:50176
	ds_read_b128 v[212:215], v151 offset:51200
	ds_read_b128 v[216:219], v151 offset:52224
	ds_read_b128 v[220:223], v151 offset:53248
	ds_read_b128 v[224:227], v151 offset:54272
	ds_read_b128 v[228:231], v151 offset:55296
	ds_read_b128 v[244:247], v151 offset:56320
	global_load_lds_dwordx4 v[164:165], off
	s_add_i32 m0, s10, 0x2000
	s_add_u32 s10, s24, 0xb0080
	v_lshl_add_u64 v[164:165], v[232:233], 0, s[56:57]
	s_addc_u32 s11, s25, 0
	s_add_i32 s24, s54, s30
	global_load_lds_dwordx4 v[164:165], off
	v_lshl_add_u64 v[164:165], s[10:11], 0, v[0:1]
	s_mov_b32 m0, s24
	s_nop 0
	global_load_lds_dwordx4 v[164:165], off
	v_lshl_add_u64 v[164:165], s[10:11], 0, v[134:135]
	s_add_i32 m0, s24, 0x2000
	s_nop 0
	global_load_lds_dwordx4 v[164:165], off
	v_lshl_add_u64 v[164:165], v[236:237], 0, s[56:57]
	s_mov_b32 m0, s41
	s_nop 0
	global_load_lds_dwordx4 v[164:165], off
	v_lshl_add_u64 v[164:165], v[248:249], 0, s[56:57]
	s_mov_b32 m0, s42
	s_nop 0
	global_load_lds_dwordx4 v[164:165], off
	s_waitcnt vmcnt(8)
	s_waitcnt lgkmcnt(0)
	s_barrier
	s_setprio 1
	s_waitcnt lgkmcnt(0)
	v_mfma_f32_16x16x32_bf16 v[62:65], v[140:143], v[204:207], v[62:65]
	v_mfma_f32_16x16x32_bf16 v[58:61], v[152:155], v[204:207], v[58:61]
	v_mfma_f32_16x16x32_bf16 v[46:49], v[140:143], v[212:215], v[46:49]
	v_mfma_f32_16x16x32_bf16 v[42:45], v[152:155], v[212:215], v[42:45]
	v_mfma_f32_16x16x32_bf16 v[30:33], v[140:143], v[220:223], v[30:33]
	v_mfma_f32_16x16x32_bf16 v[26:29], v[152:155], v[220:223], v[26:29]
	v_mfma_f32_16x16x32_bf16 v[14:17], v[140:143], v[228:231], v[14:17]
	v_mfma_f32_16x16x32_bf16 v[10:13], v[152:155], v[228:231], v[10:13]
	v_mfma_f32_16x16x32_bf16 v[62:65], v[144:147], v[208:211], v[62:65]
	v_mfma_f32_16x16x32_bf16 v[58:61], v[156:159], v[208:211], v[58:61]
	v_mfma_f32_16x16x32_bf16 v[46:49], v[144:147], v[216:219], v[46:49]
	v_mfma_f32_16x16x32_bf16 v[42:45], v[156:159], v[216:219], v[42:45]
	v_mfma_f32_16x16x32_bf16 v[30:33], v[144:147], v[224:227], v[30:33]
	v_mfma_f32_16x16x32_bf16 v[26:29], v[156:159], v[224:227], v[26:29]
	v_mfma_f32_16x16x32_bf16 v[14:17], v[144:147], v[244:247], v[14:17]
	v_mfma_f32_16x16x32_bf16 v[10:13], v[156:159], v[244:247], v[10:13]
	s_setprio 0
	s_setprio 1
	v_mfma_f32_16x16x32_bf16 v[54:57], v[160:163], v[204:207], v[54:57]
	v_mfma_f32_16x16x32_bf16 v[50:53], v[196:199], v[204:207], v[50:53]
	v_mfma_f32_16x16x32_bf16 v[38:41], v[160:163], v[212:215], v[38:41]
	v_mfma_f32_16x16x32_bf16 v[34:37], v[196:199], v[212:215], v[34:37]
	v_mfma_f32_16x16x32_bf16 v[22:25], v[160:163], v[220:223], v[22:25]
	v_mfma_f32_16x16x32_bf16 v[18:21], v[196:199], v[220:223], v[18:21]
	v_mfma_f32_16x16x32_bf16 v[6:9], v[160:163], v[228:231], v[6:9]
	v_mfma_f32_16x16x32_bf16 v[2:5], v[196:199], v[228:231], v[2:5]
	v_mfma_f32_16x16x32_bf16 v[54:57], v[192:195], v[208:211], v[54:57]
	v_mfma_f32_16x16x32_bf16 v[50:53], v[200:203], v[208:211], v[50:53]
	v_mfma_f32_16x16x32_bf16 v[38:41], v[192:195], v[216:219], v[38:41]
	v_mfma_f32_16x16x32_bf16 v[34:37], v[200:203], v[216:219], v[34:37]
	v_mfma_f32_16x16x32_bf16 v[22:25], v[192:195], v[224:227], v[22:25]
	s_setprio 3
	s_barrier
	v_mfma_f32_16x16x32_bf16 v[18:21], v[200:203], v[224:227], v[18:21]
	v_mfma_f32_16x16x32_bf16 v[6:9], v[192:195], v[244:247], v[6:9]
	v_mfma_f32_16x16x32_bf16 v[2:5], v[200:203], v[244:247], v[2:5]
	s_setprio 0
	s_add_i32 s52, s52, 2
	s_add_u32 s50, s50, 0x100
	s_addc_u32 s51, s51, 0
	s_cmp_gt_u32 s52, 41
	s_mov_b64 s[10:11], s[22:23]
	s_cbranch_scc0 .LBB0_839
	s_and_b64 vcc, exec, s[16:17]
	s_cbranch_vccz .LBB0_842
	s_barrier
